# HGRN128/HGRN64 scan loops: counted vmcnt(8/7) at loop head + explicit waits in odd step, vmcnt(0) peeled to preheader
# speedup vs baseline: 1.0083x; 1.0018x over previous
.LBB0_850:
	s_and_b64 s[4:5], s[80:81], exec
	s_movk_i32 s3, 0x400
	s_cselect_b32 s74, s3, 0x100
	s_ashr_i32 s3, s91, 3
	s_lshl_b32 s4, s3, 10
	s_bfe_u32 s59, s91, 0x20001
	s_and_b32 s58, s91, 1
	s_add_i32 s6, s4, 0x2000
	s_lshl_b32 s3, s3, 8
	s_and_b64 s[4:5], s[80:81], exec
	s_cselect_b32 s73, s6, s3
	s_cmp_eq_u32 s58, 0
	s_cselect_b64 s[4:5], -1, 0
	s_and_b64 s[6:7], s[4:5], exec
	s_mov_b32 s3, 0xbd22000
	s_cselect_b32 s3, s3, 0xd522000
	s_add_u32 s28, s24, s3
	s_addc_u32 s76, s25, 0
	s_and_b32 s3, s91, -8
	s_lshl_b32 s6, s58, 2
	s_or_b32 s3, s6, s3
	s_or_b32 s56, s3, s59
	s_ashr_i32 s57, s56, 31
	s_cmp_lt_i32 s92, 0
	s_mov_b64 s[82:83], -1
	s_cbranch_scc0 .LBB0_879
	s_xor_b64 s[6:7], s[0:1], -1
	s_xor_b64 s[62:63], s[80:81], -1
	s_andn2_b64 vcc, exec, s[6:7]
	s_mov_b64 s[6:7], -1
	s_cbranch_vccnz .LBB0_865
	s_lshl_b64 s[82:83], s[56:57], 16
	s_add_u32 s3, s40, s82
	s_addc_u32 s8, s41, s83
	s_and_b64 s[6:7], s[80:81], exec
	s_cselect_b32 s15, s8, 0
	s_cselect_b32 s14, s3, 0
	s_lshl_b32 s3, s59, 8
	s_add_u32 s8, s60, s3
	s_addc_u32 s9, s61, 0
	v_readlane_b32 s6, v254, 40
	s_add_u32 s10, s6, s3
	v_readlane_b32 s6, v254, 41
	s_addc_u32 s11, s6, 0
	s_lshl_b32 s6, s58, 10
	s_add_u32 s6, s84, s6
	s_addc_u32 s7, s85, 0
	s_add_u32 s6, s6, s3
	s_addc_u32 s7, s7, 0
	s_add_u32 s96, s28, s3
	s_addc_u32 s97, s76, 0
	s_lshr_b32 s35, s74, 5
	v_mov_b32_e32 v1, v224
	s_cmp_eq_u64 s[14:15], 0
	s_cselect_b64 s[12:13], -1, 0
	v_ashrrev_i32_e32 v3, 6, v1
	s_waitcnt vmcnt(2)
	v_lshrrev_b32_e32 v4, 2, v1
	v_and_b32_e32 v190, 15, v1
	v_lshlrev_b32_e32 v0, 4, v3
	v_and_b32_e32 v5, 8, v4
	s_movk_i32 s3, 0x70
	s_and_b64 s[16:17], s[12:13], exec
	v_and_or_b32 v64, v0, s3, v5
	v_or_b32_e32 v120, v0, v190
	v_and_b32_e32 v66, 12, v4
	s_cselect_b32 s3, s41, s15
	s_cselect_b32 s14, s40, s14
	v_ashrrev_i32_e32 v121, 31, v120
	v_lshlrev_b32_e32 v128, 9, v66
	v_mov_b32_e32 v4, s14
	v_mov_b32_e32 v5, s3
	v_or_b32_e32 v152, 0xe000, v128
	v_mov_b32_e32 v153, v2
	v_lshl_add_u64 v[4:5], v[120:121], 2, v[4:5]
	v_or_b32_e32 v144, 0xc000, v128
	v_mov_b32_e32 v145, v2
	v_or_b32_e32 v146, 0xc200, v128
	v_mov_b32_e32 v147, v2
	v_or_b32_e32 v148, 0xc400, v128
	v_mov_b32_e32 v149, v2
	v_or_b32_e32 v150, 0xc600, v128
	v_mov_b32_e32 v151, v2
	v_or_b32_e32 v154, 0xe200, v128
	v_mov_b32_e32 v155, v2
	v_or_b32_e32 v156, 0xe400, v128
	v_mov_b32_e32 v157, v2
	v_or_b32_e32 v158, 0xe600, v128
	v_mov_b32_e32 v159, v2
	v_lshl_add_u64 v[6:7], v[4:5], 0, v[152:153]
	v_lshl_add_u64 v[8:9], v[4:5], 0, v[154:155]
	v_lshl_add_u64 v[10:11], v[4:5], 0, v[156:157]
	v_lshl_add_u64 v[12:13], v[4:5], 0, v[158:159]
	v_lshl_add_u64 v[14:15], v[4:5], 0, v[144:145]
	v_lshl_add_u64 v[16:17], v[4:5], 0, v[146:147]
	v_lshl_add_u64 v[18:19], v[4:5], 0, v[148:149]
	v_lshl_add_u64 v[20:21], v[4:5], 0, v[150:151]
	global_load_dword v22, v[6:7], off
	global_load_dword v23, v[8:9], off
	global_load_dword v24, v[10:11], off
	global_load_dword v25, v[12:13], off
	global_load_dword v26, v[14:15], off
	global_load_dword v27, v[16:17], off
	global_load_dword v34, v[18:19], off
	global_load_dword v35, v[20:21], off
	v_or_b32_e32 v138, 0xa000, v128
	v_mov_b32_e32 v139, v2
	v_or_b32_e32 v140, 0xa200, v128
	v_mov_b32_e32 v141, v2
	v_or_b32_e32 v142, 0xa400, v128
	v_mov_b32_e32 v143, v2
	v_lshl_add_u64 v[6:7], v[4:5], 0, v[138:139]
	v_or_b32_e32 v160, 0xa600, v128
	v_mov_b32_e32 v161, v2
	v_lshl_add_u64 v[8:9], v[4:5], 0, v[140:141]
	v_lshl_add_u64 v[10:11], v[4:5], 0, v[142:143]
	global_load_dword v36, v[6:7], off
	global_load_dword v37, v[8:9], off
	global_load_dword v38, v[10:11], off
	v_or_b32_e32 v176, 0x6000, v128
	v_mov_b32_e32 v177, v2
	v_or_b32_e32 v168, 0x8000, v128
	v_mov_b32_e32 v169, v2
	v_or_b32_e32 v166, 0x8200, v128
	v_mov_b32_e32 v167, v2
	v_or_b32_e32 v164, 0x8400, v128
	v_mov_b32_e32 v165, v2
	v_or_b32_e32 v162, 0x8600, v128
	v_mov_b32_e32 v163, v2
	v_lshl_add_u64 v[6:7], v[4:5], 0, v[160:161]
	v_or_b32_e32 v122, 0x2000, v128
	v_mov_b32_e32 v123, v2
	v_or_b32_e32 v132, 0x4000, v128
	v_mov_b32_e32 v133, v2
	v_or_b32_e32 v134, 0x4200, v128
	v_mov_b32_e32 v135, v2
	v_or_b32_e32 v136, 0x4400, v128
	v_mov_b32_e32 v137, v2
	v_or_b32_e32 v178, 0x4600, v128
	v_mov_b32_e32 v179, v2
	v_or_b32_e32 v174, 0x6200, v128
	v_mov_b32_e32 v175, v2
	v_or_b32_e32 v172, 0x6400, v128
	v_mov_b32_e32 v173, v2
	v_or_b32_e32 v170, 0x6600, v128
	v_mov_b32_e32 v171, v2
	v_lshl_add_u64 v[8:9], v[4:5], 0, v[168:169]
	v_lshl_add_u64 v[10:11], v[4:5], 0, v[166:167]
	v_lshl_add_u64 v[12:13], v[4:5], 0, v[164:165]
	v_lshl_add_u64 v[14:15], v[4:5], 0, v[162:163]
	global_load_dword v39, v[6:7], off
	global_load_dword v40, v[8:9], off
	global_load_dword v41, v[10:11], off
	global_load_dword v42, v[12:13], off
	global_load_dword v43, v[14:15], off
	v_lshl_add_u64 v[6:7], v[4:5], 0, v[176:177]
	v_mov_b32_e32 v129, v2
	v_or_b32_e32 v124, 0x2200, v128
	v_mov_b32_e32 v125, v2
	v_or_b32_e32 v126, 0x2400, v128
	v_mov_b32_e32 v127, v2
	v_or_b32_e32 v130, 0x2600, v128
	v_mov_b32_e32 v131, v2
	v_lshl_add_u64 v[8:9], v[4:5], 0, v[174:175]
	v_lshl_add_u64 v[10:11], v[4:5], 0, v[172:173]
	v_lshl_add_u64 v[12:13], v[4:5], 0, v[170:171]
	v_lshl_add_u64 v[14:15], v[4:5], 0, v[132:133]
	v_lshl_add_u64 v[16:17], v[4:5], 0, v[134:135]
	v_lshl_add_u64 v[18:19], v[4:5], 0, v[136:137]
	v_lshl_add_u64 v[20:21], v[4:5], 0, v[178:179]
	global_load_dword v44, v[6:7], off
	global_load_dword v45, v[8:9], off
	global_load_dword v46, v[10:11], off
	global_load_dword v47, v[12:13], off
	global_load_dword v48, v[14:15], off
	global_load_dword v49, v[16:17], off
	global_load_dword v50, v[18:19], off
	global_load_dword v51, v[20:21], off
	v_lshl_add_u64 v[6:7], v[4:5], 0, v[122:123]
	s_movk_i32 s3, 0xffdf
	v_and_b32_e32 v191, 31, v1
	v_lshl_add_u64 v[8:9], v[4:5], 0, v[124:125]
	v_lshl_add_u64 v[10:11], v[4:5], 0, v[126:127]
	v_lshl_add_u64 v[12:13], v[4:5], 0, v[130:131]
	v_lshl_add_u64 v[4:5], v[4:5], 0, v[128:129]
	global_load_dword v52, v[6:7], off
	global_load_dword v53, v[8:9], off
	global_load_dword v54, v[10:11], off
	global_load_dword v55, v[12:13], off
	global_load_dword v56, v[4:5], off
	global_load_dword v57, v[4:5], off offset:512
	global_load_dword v58, v[4:5], off offset:1024
	global_load_dword v59, v[4:5], off offset:1536
	v_bitop3_b32 v7, v1, s3, 31 bitop3:0x6c
	v_ashrrev_i32_e32 v192, 4, v1
	v_or_b32_e32 v6, 32, v191
	v_add_u32_e32 v7, s74, v7
	v_lshlrev_b32_e32 v4, 4, v1
	v_sub_u32_e32 v5, s74, v192
	v_cndmask_b32_e64 v6, v7, v6, s[4:5]
	v_and_b32_e32 v62, 0xf0, v4
	v_add_u32_e32 v4, 32, v192
	v_subrev_u32_e32 v5, 33, v5
	v_add_u32_e32 v10, s73, v6
	v_cndmask_b32_e64 v4, v5, v4, s[4:5]
	v_ashrrev_i32_e32 v11, 31, v10
	v_mov_b32_e32 v63, v2
	v_add_u32_e32 v4, s73, v4
	v_mov_b64_e32 v[8:9], s[10:11]
	v_lshlrev_b64 v[6:7], 11, v[10:11]
	v_lshlrev_b32_e32 v60, 1, v64
	v_mov_b32_e32 v61, v2
	v_lshl_add_u64 v[184:185], s[10:11], 0, v[62:63]
	v_mad_i64_i32 v[4:5], s[10:11], v4, s89, v[8:9]
	v_lshl_add_u64 v[6:7], s[6:7], 0, v[6:7]
	v_xad_u32 v18, v191, -1, s74
	v_lshl_add_u64 v[4:5], v[4:5], 0, v[62:63]
	v_lshl_add_u64 v[12:13], v[6:7], 0, v[60:61]
	v_cndmask_b32_e64 v18, v18, v191, s[4:5]
	s_waitcnt vmcnt(31)
	v_cndmask_b32_e64 v28, v22, 0, s[12:13]
	s_waitcnt vmcnt(30)
	v_cndmask_b32_e64 v29, v23, 0, s[12:13]
	global_load_dwordx4 v[4:7], v[4:5], off
	s_nop 0
	global_load_dwordx4 v[20:23], v[12:13], off
	v_xad_u32 v12, v192, -1, s74
	v_add_u32_e32 v18, s73, v18
	v_cndmask_b32_e64 v12, v12, v192, s[4:5]
	v_ashrrev_i32_e32 v19, 31, v18
	s_waitcnt vmcnt(31)
	v_cndmask_b32_e64 v30, v24, 0, s[12:13]
	s_waitcnt vmcnt(30)
	v_cndmask_b32_e64 v31, v25, 0, s[12:13]
	v_mov_b64_e32 v[16:17], s[8:9]
	v_add_u32_e32 v12, s73, v12
	v_lshlrev_b64 v[24:25], 11, v[18:19]
	v_lshl_add_u64 v[180:181], s[8:9], 0, v[60:61]
	v_lshl_add_u64 v[182:183], s[6:7], 0, v[60:61]
	v_mad_i64_i32 v[10:11], s[8:9], v10, s89, v[16:17]
	v_mad_i64_i32 v[8:9], s[8:9], v12, s89, v[8:9]
	v_lshl_add_u64 v[24:25], s[6:7], 0, v[24:25]
	v_mad_i64_i32 v[16:17], s[6:7], v18, s89, v[16:17]
	v_lshl_add_u64 v[10:11], v[10:11], 0, v[60:61]
	v_lshl_add_u64 v[8:9], v[8:9], 0, v[62:63]
	v_lshl_add_u64 v[24:25], v[24:25], 0, v[60:61]
	v_lshl_add_u64 v[16:17], v[16:17], 0, v[60:61]
	s_waitcnt vmcnt(29)
	v_cndmask_b32_e64 v32, v26, 0, s[12:13]
	s_waitcnt vmcnt(28)
	v_cndmask_b32_e64 v33, v27, 0, s[12:13]
	global_load_dwordx4 v[12:15], v[10:11], off
	s_nop 0
	global_load_dwordx4 v[8:11], v[8:9], off
	s_nop 0
	global_load_dwordx4 v[24:27], v[24:25], off
	s_nop 0
	global_load_dwordx4 v[16:19], v[16:17], off
	v_lshlrev_b32_e32 v65, 3, v1
	v_lshlrev_b32_e32 v63, 2, v64
	v_lshlrev_b32_e32 v64, 2, v1
	s_movk_i32 s3, 0xfc
	v_and_or_b32 v193, v64, s71, 60
	v_bitop3_b32 v194, v64, s3, v188 bitop3:0xc8
	v_bitop3_b32 v64, v65, s71, v65 bitop3:0xc
	v_add_u32_e32 v61, 0, v60
	v_lshlrev_b32_e32 v64, 2, v64
	v_add3_u32 v195, v61, v60, v64
	v_mul_u32_u24_e32 v60, 0x88, v191
	s_movk_i32 s3, 0x110
	v_lshl_add_u32 v196, v60, 1, v61
	v_mul_lo_u32 v60, v192, s3
	v_add3_u32 v197, 0, v62, v60
	v_lshlrev_b32_e32 v62, 2, v66
	v_readlane_b32 s16, v254, 54
	v_bfe_u32 v1, v1, 2, 4
	v_mul_u32_u24_e32 v1, 0x88, v1
	v_add_u32_e32 v210, s16, v62
	v_readlane_b32 s16, v254, 55
	v_lshlrev_b32_e32 v60, 1, v1
	v_and_b32_e32 v61, 24, v65
	v_add_u32_e32 v211, s16, v62
	v_readlane_b32 s16, v254, 56
	v_add3_u32 v198, 0, v60, v61
	v_or_b32_e32 v61, 2, v66
	v_add_u32_e32 v212, s16, v62
	v_readlane_b32 s16, v254, 57
	s_waitcnt vmcnt(31)
	v_cndmask_b32_e64 v34, v34, 0, s[12:13]
	s_waitcnt vmcnt(30)
	v_cndmask_b32_e64 v35, v35, 0, s[12:13]
	v_add_u32_e32 v213, s16, v62
	v_readlane_b32 s16, v254, 58
	s_waitcnt vmcnt(29)
	v_cndmask_b32_e64 v36, v36, 0, s[12:13]
	s_waitcnt vmcnt(28)
	v_cndmask_b32_e64 v37, v37, 0, s[12:13]
	s_waitcnt vmcnt(27)
	v_cndmask_b32_e64 v38, v38, 0, s[12:13]
	s_waitcnt vmcnt(26)
	v_cndmask_b32_e64 v39, v39, 0, s[12:13]
	s_waitcnt vmcnt(25)
	v_cndmask_b32_e64 v40, v40, 0, s[12:13]
	s_waitcnt vmcnt(24)
	v_cndmask_b32_e64 v41, v41, 0, s[12:13]
	s_waitcnt vmcnt(23)
	v_cndmask_b32_e64 v42, v42, 0, s[12:13]
	s_waitcnt vmcnt(22)
	v_cndmask_b32_e64 v43, v43, 0, s[12:13]
	s_waitcnt vmcnt(21)
	v_cndmask_b32_e64 v44, v44, 0, s[12:13]
	s_waitcnt vmcnt(20)
	v_cndmask_b32_e64 v45, v45, 0, s[12:13]
	s_waitcnt vmcnt(19)
	v_cndmask_b32_e64 v46, v46, 0, s[12:13]
	s_waitcnt vmcnt(18)
	v_cndmask_b32_e64 v47, v47, 0, s[12:13]
	s_waitcnt vmcnt(17)
	v_cndmask_b32_e64 v48, v48, 0, s[12:13]
	s_waitcnt vmcnt(16)
	v_cndmask_b32_e64 v49, v49, 0, s[12:13]
	s_waitcnt vmcnt(15)
	v_cndmask_b32_e64 v50, v50, 0, s[12:13]
	s_waitcnt vmcnt(14)
	v_cndmask_b32_e64 v51, v51, 0, s[12:13]
	s_waitcnt vmcnt(13)
	v_cndmask_b32_e64 v52, v52, 0, s[12:13]
	s_waitcnt vmcnt(12)
	v_cndmask_b32_e64 v53, v53, 0, s[12:13]
	s_waitcnt vmcnt(11)
	v_cndmask_b32_e64 v54, v54, 0, s[12:13]
	s_waitcnt vmcnt(10)
	v_cndmask_b32_e64 v55, v55, 0, s[12:13]
	s_waitcnt vmcnt(9)
	v_cndmask_b32_e64 v56, v56, 0, s[12:13]
	s_waitcnt vmcnt(8)
	v_cndmask_b32_e64 v57, v57, 0, s[12:13]
	s_waitcnt vmcnt(7)
	v_cndmask_b32_e64 v58, v58, 0, s[12:13]
	s_waitcnt vmcnt(6)
	v_cndmask_b32_e64 v59, v59, 0, s[12:13]
	v_ashrrev_i32_e32 v1, 31, v0
	v_cmp_gt_u32_e64 s[12:13], v61, v190
	v_or_b32_e32 v61, 3, v66
	v_add_u32_e32 v218, s16, v62
	v_readlane_b32 s16, v254, 59
	v_cmp_gt_i32_e32 vcc, 8, v3
	v_lshl_add_u32 v199, v3, 5, v198
	v_lshlrev_b32_e32 v60, 1, v66
	v_mul_u32_u24_e32 v3, 0x88, v190
	v_cmp_gt_u32_e64 s[14:15], v61, v190
	v_add_u32_e32 v202, 0, v62
	v_lshl_add_u64 v[0:1], v[0:1], 1, s[96:97]
	v_mov_b32_e32 v61, v2
	v_add_u32_e32 v219, s16, v62
	v_readlane_b32 s16, v254, 60
	v_lshlrev_b32_e32 v3, 1, v3
	v_lshl_add_u64 v[186:187], v[0:1], 0, v[60:61]
	v_sub_u32_e32 v0, v202, v60
	v_add_u32_e32 v220, s16, v62
	v_readlane_b32 s16, v254, 61
	s_mov_b32 s77, 3
	v_cmp_eq_u32_e64 s[6:7], 15, v190
	s_add_i32 s3, s35, -1
	v_add3_u32 v200, 0, v60, v3
	v_add3_u32 v201, 0, v3, v60
	v_cmp_gt_u32_e64 s[8:9], v66, v190
	v_cmp_lt_u32_e64 s[10:11], v66, v190
	v_add3_u32 v203, s88, v63, v64
	v_add_u32_e32 v204, 0xf200, v199
	v_add_u32_e32 v205, v0, v3
	v_add_u32_e32 v206, s72, v62
	v_add_u32_e32 v207, s75, v62
	v_add_u32_e32 v208, s18, v62
	v_add_u32_e32 v209, s19, v62
	v_add_u32_e32 v214, s88, v62
	v_add_u32_e32 v215, s70, v62
	v_add_u32_e32 v216, s29, v62
	v_add_u32_e32 v217, s68, v62
	v_add_u32_e32 v221, s16, v62
	v_xad_u32 v222, v190, -1, s74
	s_waitcnt vmcnt(0)
	s_branch .LBB0_855

.LBB0_854:
	s_or_b64 exec, exec, s[96:97]
	s_min_i32 s16, s77, s3
	s_lshl_b32 s16, s16, 5
	v_or_b32_e32 v0, s16, v191
	v_xad_u32 v1, v0, -1, s74
	v_cndmask_b32_e64 v0, v1, v0, s[4:5]
	v_add_u32_e32 v1, s16, v192
	v_xad_u32 v3, v1, -1, s74
	v_add_u32_e32 v0, s73, v0
	v_cndmask_b32_e64 v3, v3, v1, s[4:5]
	v_ashrrev_i32_e32 v1, 31, v0
	s_waitcnt vmcnt(7)
	ds_write_b128 v197, v[4:7] offset:61952
	v_mad_i64_i32 v[4:5], s[16:17], v0, s89, v[180:181]
	v_lshlrev_b64 v[0:1], 11, v[0:1]
	v_lshl_add_u64 v[0:1], v[182:183], 0, v[0:1]
	global_load_dwordx4 v[12:15], v[4:5], off
	global_load_dwordx4 v[20:23], v[0:1], off
	v_add_u32_e32 v0, s73, v3
	v_mad_i64_i32 v[0:1], s[16:17], v0, s89, v[184:185]
	global_load_dwordx4 v[4:7], v[0:1], off
	v_add_u32_e32 v0, 0x8800, v205
	s_waitcnt lgkmcnt(0)
	s_barrier
	ds_read_b64_tr_b16 v[92:93], v204
	ds_read_b64_tr_b16 v[94:95], v204 offset:4352
	ds_read_b64 v[88:89], v0 offset:1024
	ds_read_b64 v[90:91], v0 offset:1056
	ds_read_b64 v[80:81], v0 offset:1088
	ds_read_b64 v[82:83], v0 offset:1120
	ds_read_b64 v[72:73], v0 offset:1152
	ds_read_b64 v[74:75], v0 offset:1184
	ds_read_b64 v[60:61], v0 offset:1216
	ds_read_b64 v[62:63], v0 offset:1248
	v_add_u32_e32 v0, 0x9800, v205
	v_add_u32_e32 v1, 0xb800, v201
	ds_read_b64 v[84:85], v0 offset:1280
	ds_read_b64 v[86:87], v0 offset:1312
	ds_read_b64 v[76:77], v0 offset:1344
	ds_read_b64 v[78:79], v0 offset:1376
	ds_read_b64 v[68:69], v0 offset:1408
	ds_read_b64 v[70:71], v0 offset:1440
	ds_read_b64 v[64:65], v0 offset:1472
	ds_read_b64 v[66:67], v0 offset:1504
	ds_read_b64 v[100:101], v1 offset:1792
	ds_read_b64 v[102:103], v1 offset:1824
	v_add_u32_e32 v0, 0xa800, v201
	ds_read_b64 v[96:97], v0 offset:1536
	ds_read_b64 v[98:99], v0 offset:1568
	ds_read_b64 v[108:109], v0 offset:1600
	ds_read_b64 v[110:111], v0 offset:1632
	ds_read_b64 v[112:113], v1 offset:1856
	ds_read_b64 v[114:115], v1 offset:1888
	s_waitcnt lgkmcnt(6)
	v_mfma_f32_16x16x32_bf16 v[100:103], v[100:103], v[84:87], 0
	s_add_i32 s77, s77, 2
	v_subrev_u32_e32 v222, 64, v222
	s_cmp_ge_u32 s78, s35
	s_waitcnt lgkmcnt(4)
	v_mfma_f32_16x16x32_bf16 v[104:107], v[96:99], v[88:91], 0
	s_waitcnt lgkmcnt(0)
	v_mfma_f32_16x16x32_bf16 v[100:103], v[112:115], v[76:79], v[100:103]
	ds_read_b64 v[112:113], v0 offset:1664
	ds_read_b64 v[114:115], v0 offset:1696
	ds_read_b64 v[116:117], v1 offset:1920
	ds_read_b64 v[118:119], v1 offset:1952
	v_mfma_f32_16x16x32_bf16 v[104:107], v[108:111], v[80:83], v[104:107]
	s_waitcnt lgkmcnt(0)
	v_mfma_f32_16x16x32_bf16 v[100:103], v[116:119], v[68:71], v[100:103]
	ds_read_b64 v[116:117], v0 offset:1728
	ds_read_b64 v[118:119], v0 offset:1760
	ds_read_b64 v[226:227], v1 offset:1984
	ds_read_b64 v[228:229], v1 offset:2016
	v_mov_b32_e32 v0, s93
	v_mfma_f32_16x16x32_bf16 v[96:99], v[96:99], v[84:87], 0
	v_mfma_f32_16x16x32_bf16 v[104:107], v[112:115], v[72:75], v[104:107]
	v_mfma_f32_16x16x32_bf16 v[96:99], v[108:111], v[76:79], v[96:99]
	s_waitcnt lgkmcnt(2)
	v_mfma_f32_16x16x32_bf16 v[104:107], v[116:119], v[60:63], v[104:107]
	s_waitcnt lgkmcnt(0)
	v_mfma_f32_16x16x32_bf16 v[100:103], v[226:229], v[64:67], v[100:103]
	v_mov_b32_e32 v226, s93
	s_nop 4
	v_cndmask_b32_e64 v0, v104, v0, s[8:9]
	v_cndmask_b32_e64 v0, v0, v104, s[10:11]
	v_mfma_f32_16x16x32_bf16 v[96:99], v[112:115], v[68:71], v[96:99]
	v_cndmask_b32_e64 v3, v106, 0, s[12:13]
	v_cndmask_b32_e64 v1, v100, v226, s[8:9]
	v_cndmask_b32_e64 v100, v1, v100, s[10:11]
	v_cndmask_b32_e64 v1, 0, v105, s[10:11]
	v_cndmask_b32_e64 v104, v107, 0, s[14:15]
	v_cvt_pk_bf16_f32 v0, v0, v1
	v_cvt_pk_bf16_f32 v1, v3, v104
	ds_read_b128 v[104:107], v206
	ds_read_b128 v[108:111], v207
	v_mfma_f32_16x16x32_bf16 v[96:99], v[116:119], v[64:67], v[96:99]
	v_cndmask_b32_e64 v101, 0, v101, s[10:11]
	v_cndmask_b32_e64 v102, v102, 0, s[12:13]
	v_cndmask_b32_e64 v103, v103, 0, s[14:15]
	v_mov_b32_e32 v3, v2
	s_waitcnt lgkmcnt(0)
	v_pk_mul_f32 v[110:111], v[54:55], v[110:111]
	s_nop 1
	v_cvt_pk_bf16_f32 v96, v96, v97
	v_cvt_pk_bf16_f32 v97, v98, v99
	v_cvt_pk_bf16_f32 v98, v100, v101
	v_cvt_pk_bf16_f32 v99, v102, v103
	v_mfma_f32_16x16x32_bf16 v[100:103], v[92:95], v[0:3], 0
	v_mul_f32_e64 v0, v58, v106
	v_mul_f32_e64 v1, v59, v107
	v_pk_mul_f32 v[106:107], v[52:53], v[108:109]
	v_pk_mul_f32 v[104:105], v[56:57], v[104:105]
	v_cvt_pk_bf16_f32 v106, v106, v107
	v_cvt_pk_bf16_f32 v107, v110, v111
	ds_read_b128 v[108:111], v208
	ds_read_b128 v[112:115], v209
	v_cvt_pk_bf16_f32 v104, v104, v105
	v_cvt_pk_bf16_f32 v105, v0, v1
	v_mfma_f32_16x16x32_bf16 v[96:99], v[92:95], v[96:99], 0
	s_waitcnt lgkmcnt(1)
	v_pk_mul_f32 v[0:1], v[50:51], v[110:111]
	v_pk_mul_f32 v[108:109], v[48:49], v[108:109]
	s_waitcnt lgkmcnt(0)
	v_pk_mul_f32 v[110:111], v[46:47], v[114:115]
	v_pk_mul_f32 v[112:113], v[44:45], v[112:113]
	v_cvt_pk_bf16_f32 v116, v108, v109
	v_cvt_pk_bf16_f32 v118, v112, v113
	v_cvt_pk_bf16_f32 v119, v110, v111
	ds_read_b128 v[108:111], v210
	ds_read_b128 v[112:115], v211
	v_cvt_pk_bf16_f32 v117, v0, v1
	v_mfma_f32_16x16x32_bf16 v[88:91], v[104:107], v[88:91], v[100:103]
	v_xor_b32_e32 v3, 0xffffffdf, v190
	s_waitcnt lgkmcnt(1)
	v_pk_mul_f32 v[0:1], v[42:43], v[110:111]
	s_waitcnt lgkmcnt(0)
	v_pk_mul_f32 v[114:115], v[38:39], v[114:115]
	v_pk_mul_f32 v[110:111], v[36:37], v[112:113]
	v_pk_mul_f32 v[108:109], v[40:41], v[108:109]
	v_cvt_pk_bf16_f32 v110, v110, v111
	v_cvt_pk_bf16_f32 v111, v114, v115
	ds_read_b128 v[112:115], v212
	ds_read_b128 v[226:229], v213
	v_cvt_pk_bf16_f32 v108, v108, v109
	v_cvt_pk_bf16_f32 v109, v0, v1
	v_mfma_f32_16x16x32_bf16 v[84:87], v[104:107], v[84:87], v[96:99]
	s_waitcnt lgkmcnt(1)
	v_pk_mul_f32 v[0:1], v[34:35], v[114:115]
	s_waitcnt lgkmcnt(0)
	v_pk_mul_f32 v[228:229], v[30:31], v[228:229]
	v_pk_mul_f32 v[114:115], v[28:29], v[226:227]
	v_mfma_f32_16x16x32_bf16 v[80:83], v[116:119], v[80:83], v[88:91]
	v_cvt_pk_bf16_f32 v114, v114, v115
	v_cvt_pk_bf16_f32 v115, v228, v229
	ds_read_b128 v[226:229], v214
	ds_read_b64_tr_b16 v[232:233], v198 offset:57600
	ds_read_b64_tr_b16 v[230:231], v198 offset:53248
	ds_read_b64_tr_b16 v[234:235], v198 offset:53280
	v_pk_mul_f32 v[112:113], v[32:33], v[112:113]
	s_waitcnt lgkmcnt(3)
	v_pk_mul_f32 v[58:59], v[58:59], v[228:229]
	v_pk_mul_f32 v[56:57], v[56:57], v[226:227]
	ds_read_b128 v[226:229], v215
	ds_read_b64_tr_b16 v[236:237], v198 offset:57632
	s_waitcnt lgkmcnt(3)
	v_mfma_f32_16x16x32_bf16 v[56:59], v[230:233], v[92:95], v[56:59]
	v_cvt_pk_bf16_f32 v112, v112, v113
	v_cvt_pk_bf16_f32 v113, v0, v1
	s_waitcnt lgkmcnt(1)
	v_pk_mul_f32 v[54:55], v[54:55], v[228:229]
	v_pk_mul_f32 v[52:53], v[52:53], v[226:227]
	ds_read_b128 v[226:229], v216
	ds_read_b64_tr_b16 v[230:231], v198 offset:53312
	ds_read_b64_tr_b16 v[232:233], v198 offset:57664
	v_mfma_f32_16x16x32_bf16 v[76:79], v[116:119], v[76:79], v[84:87]
	v_add_u32_e32 v0, 32, v190
	s_waitcnt lgkmcnt(2)
	v_pk_mul_f32 v[50:51], v[50:51], v[228:229]
	v_pk_mul_f32 v[48:49], v[48:49], v[226:227]
	v_mfma_f32_16x16x32_bf16 v[72:75], v[108:111], v[72:75], v[80:83]
	v_add_u32_e32 v3, s74, v3
	v_cndmask_b32_e64 v3, v3, v0, s[4:5]
	v_xor_b32_e32 v0, 0xffffffcf, v190
	s_waitcnt lgkmcnt(0)
	v_mfma_f32_16x16x32_bf16 v[48:51], v[230:233], v[92:95], v[48:51]
	ds_read_b128 v[226:229], v217
	ds_read_b64_tr_b16 v[230:231], v198 offset:53344
	ds_read_b64_tr_b16 v[232:233], v198 offset:57696
	v_add_u32_e32 v1, 48, v190
	v_add_u32_e32 v0, s74, v0
	s_waitcnt lgkmcnt(2)
	v_pk_mul_f32 v[46:47], v[46:47], v[228:229]
	v_pk_mul_f32 v[44:45], v[44:45], v[226:227]
	v_mfma_f32_16x16x32_bf16 v[68:71], v[108:111], v[68:71], v[76:79]
	v_add_u32_e32 v190, 64, v190
	s_waitcnt lgkmcnt(0)
	v_mfma_f32_16x16x32_bf16 v[44:47], v[230:233], v[92:95], v[44:47]
	ds_read_b128 v[226:229], v218
	ds_read_b64_tr_b16 v[230:231], v198 offset:53376
	ds_read_b64_tr_b16 v[232:233], v198 offset:57728
	s_waitcnt lgkmcnt(2)
	v_pk_mul_f32 v[42:43], v[42:43], v[228:229]
	v_pk_mul_f32 v[40:41], v[40:41], v[226:227]
	v_mfma_f32_16x16x32_bf16 v[60:63], v[112:115], v[60:63], v[72:75]
	s_waitcnt lgkmcnt(0)
	v_mfma_f32_16x16x32_bf16 v[40:43], v[230:233], v[92:95], v[40:43]
	ds_read_b128 v[226:229], v219
	ds_read_b64_tr_b16 v[230:231], v198 offset:53408
	ds_read_b64_tr_b16 v[232:233], v198 offset:57760
	s_waitcnt lgkmcnt(2)
	v_pk_mul_f32 v[38:39], v[38:39], v[228:229]
	v_pk_mul_f32 v[36:37], v[36:37], v[226:227]
	v_mfma_f32_16x16x32_bf16 v[64:67], v[112:115], v[64:67], v[68:71]
	s_waitcnt lgkmcnt(0)
	v_mfma_f32_16x16x32_bf16 v[36:39], v[230:233], v[92:95], v[36:39]
	ds_read_b128 v[226:229], v220
	ds_read_b64_tr_b16 v[230:231], v198 offset:53440
	ds_read_b64_tr_b16 v[232:233], v198 offset:57792
	v_cndmask_b32_e64 v68, v0, v1, s[4:5]
	v_cvt_pk_bf16_f32 v1, v62, v63
	s_waitcnt lgkmcnt(2)
	v_pk_mul_f32 v[34:35], v[34:35], v[228:229]
	v_pk_mul_f32 v[32:33], v[32:33], v[226:227]
	v_add_u32_e32 v62, s73, v3
	v_ashrrev_i32_e32 v63, 31, v62
	s_waitcnt lgkmcnt(0)
	v_mfma_f32_16x16x32_bf16 v[32:35], v[230:233], v[92:95], v[32:35]
	ds_read_b128 v[226:229], v221
	ds_read_b64_tr_b16 v[230:231], v198 offset:53472
	ds_read_b64_tr_b16 v[232:233], v198 offset:57824
	v_lshlrev_b64 v[62:63], 11, v[62:63]
	v_cvt_pk_bf16_f32 v0, v60, v61
	s_waitcnt lgkmcnt(2)
	v_pk_mul_f32 v[30:31], v[30:31], v[228:229]
	v_pk_mul_f32 v[28:29], v[28:29], v[226:227]
	v_lshl_add_u64 v[62:63], v[186:187], 0, v[62:63]
	v_mfma_f32_16x16x32_bf16 v[52:55], v[234:237], v[92:95], v[52:55]
	global_store_dwordx2 v[62:63], v[0:1], off
	v_add_u32_e32 v0, s73, v68
	v_ashrrev_i32_e32 v1, 31, v0
	s_waitcnt lgkmcnt(0)
	v_mfma_f32_16x16x32_bf16 v[28:31], v[230:233], v[92:95], v[28:31]
	v_lshlrev_b64 v[0:1], 11, v[0:1]
	v_cvt_pk_bf16_f32 v60, v64, v65
	v_cvt_pk_bf16_f32 v61, v66, v67
	v_lshl_add_u64 v[0:1], v[186:187], 0, v[0:1]
	global_store_dwordx2 v[0:1], v[60:61], off
	s_cbranch_scc1 .LBB0_862
.LBB0_855:
	s_and_saveexec_b64 s[96:97], vcc
	s_cbranch_execz .LBB0_859
	s_waitcnt vmcnt(8)
	v_cvt_f32_f16_e32 v76, v24
	v_cvt_f32_f16_sdwa v75, v24 dst_sel:DWORD dst_unused:UNUSED_PAD src0_sel:WORD_1
	v_cvt_f32_f16_e32 v74, v25
	v_cvt_f32_f16_sdwa v73, v25 dst_sel:DWORD dst_unused:UNUSED_PAD src0_sel:WORD_1
	v_add_f32_dpp v0, v76, v76 row_shr:1 row_mask:0xf bank_mask:0xf bound_ctrl:1
	v_add_f32_dpp v1, v75, v75 row_shr:1 row_mask:0xf bank_mask:0xf bound_ctrl:1
	v_mov_b32_e32 v62, v2
	v_add_f32_dpp v0, v0, v0 row_shr:2 row_mask:0xf bank_mask:0xf bound_ctrl:1
	v_add_f32_dpp v1, v1, v1 row_shr:2 row_mask:0xf bank_mask:0xf bound_ctrl:1
	v_cvt_f32_f16_e32 v72, v26
	v_add_f32_dpp v0, v0, v0 row_shr:4 row_mask:0xf bank_mask:0xf bound_ctrl:1
	v_add_f32_dpp v24, v74, v74 row_shr:1 row_mask:0xf bank_mask:0xf bound_ctrl:1
	v_add_f32_dpp v1, v1, v1 row_shr:4 row_mask:0xf bank_mask:0xf bound_ctrl:1
	v_add_f32_dpp v0, v0, v0 row_shr:8 row_mask:0xf bank_mask:0xf bound_ctrl:1
	v_add_f32_dpp v24, v24, v24 row_shr:2 row_mask:0xf bank_mask:0xf bound_ctrl:1
	v_add_f32_dpp v1, v1, v1 row_shr:8 row_mask:0xf bank_mask:0xf bound_ctrl:1
	v_mov_b32_dpp v62, v0 row_bcast:15 row_mask:0xa bank_mask:0xf
	v_add_f32_e32 v78, v0, v62
	v_mov_b32_e32 v0, v2
	v_cvt_f32_f16_sdwa v71, v26 dst_sel:DWORD dst_unused:UNUSED_PAD src0_sel:WORD_1
	v_add_f32_dpp v25, v73, v73 row_shr:1 row_mask:0xf bank_mask:0xf bound_ctrl:1
	v_add_f32_dpp v24, v24, v24 row_shr:4 row_mask:0xf bank_mask:0xf bound_ctrl:1
	v_mov_b32_dpp v0, v1 row_bcast:15 row_mask:0xa bank_mask:0xf
	v_add_f32_dpp v25, v25, v25 row_shr:2 row_mask:0xf bank_mask:0xf bound_ctrl:1
	v_add_f32_dpp v24, v24, v24 row_shr:8 row_mask:0xf bank_mask:0xf bound_ctrl:1
	v_add_f32_e32 v79, v1, v0
	v_mov_b32_e32 v0, v2
	v_cvt_f32_f16_e32 v70, v27
	v_add_f32_dpp v26, v72, v72 row_shr:1 row_mask:0xf bank_mask:0xf bound_ctrl:1
	v_add_f32_dpp v25, v25, v25 row_shr:4 row_mask:0xf bank_mask:0xf bound_ctrl:1
	v_mov_b32_dpp v0, v24 row_bcast:15 row_mask:0xa bank_mask:0xf
	v_add_f32_dpp v26, v26, v26 row_shr:2 row_mask:0xf bank_mask:0xf bound_ctrl:1
	v_add_f32_dpp v25, v25, v25 row_shr:8 row_mask:0xf bank_mask:0xf bound_ctrl:1
	v_add_f32_e32 v80, v24, v0
	v_mov_b32_e32 v0, v2
	v_cvt_f32_f16_sdwa v3, v27 dst_sel:DWORD dst_unused:UNUSED_PAD src0_sel:WORD_1
	v_add_f32_dpp v27, v71, v71 row_shr:1 row_mask:0xf bank_mask:0xf bound_ctrl:1
	v_add_f32_dpp v26, v26, v26 row_shr:4 row_mask:0xf bank_mask:0xf bound_ctrl:1
	v_mov_b32_dpp v0, v25 row_bcast:15 row_mask:0xa bank_mask:0xf
	v_add_f32_dpp v27, v27, v27 row_shr:2 row_mask:0xf bank_mask:0xf bound_ctrl:1
	v_add_f32_dpp v26, v26, v26 row_shr:8 row_mask:0xf bank_mask:0xf bound_ctrl:1
	v_add_f32_e32 v81, v25, v0
	v_mov_b32_e32 v0, v2
	v_add_f32_dpp v60, v70, v70 row_shr:1 row_mask:0xf bank_mask:0xf bound_ctrl:1
	v_add_f32_dpp v27, v27, v27 row_shr:4 row_mask:0xf bank_mask:0xf bound_ctrl:1
	v_mov_b32_dpp v0, v26 row_bcast:15 row_mask:0xa bank_mask:0xf
	ds_bpermute_b32 v1, v193, v78
	v_add_f32_dpp v60, v60, v60 row_shr:2 row_mask:0xf bank_mask:0xf bound_ctrl:1
	v_add_f32_dpp v27, v27, v27 row_shr:8 row_mask:0xf bank_mask:0xf bound_ctrl:1
	v_add_f32_e32 v77, v26, v0
	v_mov_b32_e32 v0, v2
	v_add_f32_dpp v60, v60, v60 row_shr:4 row_mask:0xf bank_mask:0xf bound_ctrl:1
	v_add_f32_dpp v61, v3, v3 row_shr:1 row_mask:0xf bank_mask:0xf bound_ctrl:1
	v_mov_b32_dpp v0, v27 row_bcast:15 row_mask:0xa bank_mask:0xf
	v_add_f32_dpp v60, v60, v60 row_shr:8 row_mask:0xf bank_mask:0xf bound_ctrl:1
	v_add_f32_e32 v82, v27, v0
	v_mov_b32_e32 v0, v2
	v_add_f32_dpp v61, v61, v61 row_shr:2 row_mask:0xf bank_mask:0xf bound_ctrl:1
	ds_bpermute_b32 v26, v193, v80
	v_mov_b32_dpp v0, v60 row_bcast:15 row_mask:0xa bank_mask:0xf
	v_add_f32_e32 v83, v60, v0
	s_waitcnt lgkmcnt(1)
	v_sub_f32_e32 v0, v78, v1
	ds_bpermute_b32 v1, v193, v79
	v_med3_f32 v0, v0, s69, v189
	v_add_f32_dpp v61, v61, v61 row_shr:4 row_mask:0xf bank_mask:0xf bound_ctrl:1
	v_mul_f32_e32 v0, 0x3fb8aa3b, v0
	v_exp_f32_e32 v24, v0
	v_add_f32_dpp v61, v61, v61 row_shr:8 row_mask:0xf bank_mask:0xf bound_ctrl:1
	v_mov_b32_e32 v0, v2
	s_waitcnt lgkmcnt(0)
	v_sub_f32_e32 v1, v79, v1
	v_med3_f32 v1, v1, s69, v189
	v_mov_b32_dpp v0, v61 row_bcast:15 row_mask:0xa bank_mask:0xf
	v_add_f32_e32 v84, v61, v0
	v_mul_f32_e32 v1, 0x3fb8aa3b, v1
	v_exp_f32_e32 v25, v1
	ds_bpermute_b32 v1, v193, v81
	ds_bpermute_b32 v62, v193, v77
	ds_bpermute_b32 v63, v193, v82
	ds_bpermute_b32 v64, v193, v83
	ds_bpermute_b32 v65, v193, v84
	v_sub_f32_e32 v26, v80, v26
	s_waitcnt lgkmcnt(4)
	v_sub_f32_e32 v1, v81, v1
	s_waitcnt lgkmcnt(3)
	v_sub_f32_e32 v62, v77, v62
	s_waitcnt lgkmcnt(2)
	v_sub_f32_e32 v63, v82, v63
	s_waitcnt lgkmcnt(1)
	v_sub_f32_e32 v64, v83, v64
	s_waitcnt lgkmcnt(0)
	v_sub_f32_e32 v65, v84, v65
	v_med3_f32 v26, v26, s69, v189
	v_med3_f32 v1, v1, s69, v189
	v_med3_f32 v62, v62, s69, v189
	v_med3_f32 v63, v63, s69, v189
	v_med3_f32 v64, v64, s69, v189
	v_med3_f32 v65, v65, s69, v189
	v_mul_f32_e32 v26, 0x3fb8aa3b, v26
	v_mul_f32_e32 v1, 0x3fb8aa3b, v1
	v_mul_f32_e32 v62, 0x3fb8aa3b, v62
	v_mul_f32_e32 v63, 0x3fb8aa3b, v63
	v_mul_f32_e32 v64, 0x3fb8aa3b, v64
	v_mul_f32_e32 v65, 0x3fb8aa3b, v65
	v_exp_f32_e32 v60, v26
	v_exp_f32_e32 v61, v1
	v_exp_f32_e32 v62, v62
	v_exp_f32_e32 v63, v63
	v_exp_f32_e32 v64, v64
	v_exp_f32_e32 v65, v65
	ds_bpermute_b32 v0, v194, v24
	ds_bpermute_b32 v1, v194, v25
	ds_bpermute_b32 v26, v194, v60
	ds_bpermute_b32 v27, v194, v61
	ds_bpermute_b32 v68, v194, v62
	ds_bpermute_b32 v69, v194, v63
	ds_bpermute_b32 v66, v194, v64
	ds_bpermute_b32 v67, v194, v65
	s_and_saveexec_b64 s[16:17], s[6:7]
	s_cbranch_execz .LBB0_858
	v_mul_f32_e32 v78, 0x3fb8aa3b, v78
	v_mul_f32_e32 v79, 0x3fb8aa3b, v79
	v_mul_f32_e32 v80, 0x3fb8aa3b, v80
	v_mul_f32_e32 v81, 0x3fb8aa3b, v81
	v_exp_f32_e32 v78, v78
	v_exp_f32_e32 v79, v79
	v_exp_f32_e32 v80, v80
	v_exp_f32_e32 v81, v81
	v_mul_f32_e32 v77, 0x3fb8aa3b, v77
	ds_write_b128 v195, v[78:81] offset:34816
	v_exp_f32_e32 v78, v77
	v_mul_f32_e32 v77, 0x3fb8aa3b, v82
	v_exp_f32_e32 v79, v77
	v_mul_f32_e32 v77, 0x3fb8aa3b, v83
	v_exp_f32_e32 v80, v77
	v_mul_f32_e32 v77, 0x3fb8aa3b, v84
	v_exp_f32_e32 v81, v77
	ds_write_b128 v195, v[78:81] offset:34832
.LBB0_858:
	s_or_b64 exec, exec, s[16:17]
	v_mul_f32_e32 v75, 0x3fb8aa3b, v75
	v_mul_f32_e32 v74, 0x3fb8aa3b, v74
	v_mul_f32_e32 v73, 0x3fb8aa3b, v73
	s_waitcnt vmcnt(8)
	v_lshlrev_b32_e32 v78, 16, v16
	v_and_b32_e32 v79, 0xffff0000, v16
	v_exp_f32_e32 v77, v75
	v_exp_f32_e32 v74, v74
	v_exp_f32_e32 v75, v73
	v_rcp_f32_e32 v82, v24
	v_rcp_f32_e32 v83, v25
	v_pk_mul_f32 v[24:25], v[24:25], v[78:79]
	v_rcp_f32_e32 v78, v60
	v_rcp_f32_e32 v79, v61
	v_lshlrev_b32_e32 v16, 16, v17
	v_and_b32_e32 v17, 0xffff0000, v17
	v_mul_f32_e32 v72, 0x3fb8aa3b, v72
	v_mul_f32_e32 v71, 0x3fb8aa3b, v71
	v_exp_f32_e32 v72, v72
	v_exp_f32_e32 v73, v71
	v_pk_mul_f32 v[60:61], v[60:61], v[16:17]
	v_pk_add_f32 v[16:17], v[74:75], 1.0 op_sel_hi:[1,0] neg_lo:[1,0] neg_hi:[1,0]
	v_mul_f32_e32 v76, 0x3fb8aa3b, v76
	v_pk_mul_f32 v[74:75], v[16:17], v[78:79]
	v_rcp_f32_e32 v16, v62
	v_rcp_f32_e32 v17, v63
	v_mul_f32_e32 v70, 0x3fb8aa3b, v70
	v_mul_f32_e32 v3, 0x3fb8aa3b, v3
	v_exp_f32_e32 v76, v76
	v_exp_f32_e32 v70, v70
	v_exp_f32_e32 v71, v3
	v_pk_add_f32 v[72:73], v[72:73], 1.0 op_sel_hi:[1,0] neg_lo:[1,0] neg_hi:[1,0]
	v_lshlrev_b32_e32 v80, 16, v18
	v_pk_mul_f32 v[72:73], v[72:73], v[16:17]
	v_rcp_f32_e32 v16, v64
	v_rcp_f32_e32 v17, v65
	v_and_b32_e32 v81, 0xffff0000, v18
	v_lshlrev_b32_e32 v18, 16, v19
	v_and_b32_e32 v19, 0xffff0000, v19
	v_pk_add_f32 v[76:77], v[76:77], 1.0 op_sel_hi:[1,0] neg_lo:[1,0] neg_hi:[1,0]
	v_pk_mul_f32 v[62:63], v[62:63], v[80:81]
	v_pk_mul_f32 v[64:65], v[64:65], v[18:19]
	v_pk_add_f32 v[18:19], v[70:71], 1.0 op_sel_hi:[1,0] neg_lo:[1,0] neg_hi:[1,0]
	v_pk_mul_f32 v[76:77], v[76:77], v[82:83]
	v_pk_mul_f32 v[70:71], v[18:19], v[16:17]
	v_cvt_pk_bf16_f32 v16, v24, v25
	v_cvt_pk_bf16_f32 v17, v60, v61
	v_cvt_pk_bf16_f32 v18, v62, v63
	v_cvt_pk_bf16_f32 v19, v64, v65
	s_waitcnt lgkmcnt(6)
	v_pk_mul_f32 v[0:1], v[76:77], v[0:1]
	s_waitcnt lgkmcnt(4)
	v_pk_mul_f32 v[26:27], v[74:75], v[26:27]
	s_waitcnt lgkmcnt(2)
	v_pk_mul_f32 v[68:69], v[72:73], v[68:69]
	s_waitcnt lgkmcnt(0)
	v_pk_mul_f32 v[66:67], v[70:71], v[66:67]
	ds_write_b128 v196, v[16:19]
	v_cvt_pk_bf16_f32 v16, v76, v77
	v_cvt_pk_bf16_f32 v17, v74, v75
	v_cvt_pk_bf16_f32 v18, v72, v73
	v_cvt_pk_bf16_f32 v19, v70, v71
	ds_write_b128 v196, v[16:19] offset:8704
	v_cvt_pk_bf16_f32 v16, v0, v1
	v_cvt_pk_bf16_f32 v17, v26, v27
	v_cvt_pk_bf16_f32 v18, v68, v69
	v_cvt_pk_bf16_f32 v19, v66, v67
	ds_write_b128 v196, v[16:19] offset:17408
.LBB0_859:
	s_or_b64 exec, exec, s[96:97]
	s_add_i32 s78, s77, -1
	s_min_i32 s16, s78, s3
	s_lshl_b32 s16, s16, 5
	v_or_b32_e32 v0, s16, v191
	v_xad_u32 v1, v0, -1, s74
	v_cndmask_b32_e64 v0, v1, v0, s[4:5]
	v_add_u32_e32 v1, s16, v192
	v_xad_u32 v3, v1, -1, s74
	v_add_u32_e32 v0, s73, v0
	v_cndmask_b32_e64 v3, v3, v1, s[4:5]
	v_ashrrev_i32_e32 v1, 31, v0
	s_waitcnt vmcnt(7)
	ds_write_b128 v197, v[8:11] offset:26112
	v_mad_i64_i32 v[8:9], s[16:17], v0, s89, v[180:181]
	v_lshlrev_b64 v[0:1], 11, v[0:1]
	v_lshl_add_u64 v[0:1], v[182:183], 0, v[0:1]
	global_load_dwordx4 v[16:19], v[8:9], off
	global_load_dwordx4 v[24:27], v[0:1], off
	v_add_u32_e32 v0, s73, v3
	v_mad_i64_i32 v[0:1], s[16:17], v0, s89, v[184:185]
	global_load_dwordx4 v[8:11], v[0:1], off
	v_add_u32_e32 v0, 0x1000, v200
	v_add_u32_e32 v1, 0x3000, v201
	s_waitcnt lgkmcnt(0)
	s_barrier
	ds_read_b64_tr_b16 v[92:93], v199 offset:26112
	ds_read_b64_tr_b16 v[94:95], v199 offset:30464
	ds_read_b64 v[88:89], v200
	ds_read_b64 v[90:91], v200 offset:32
	ds_read_b64 v[80:81], v200 offset:64
	ds_read_b64 v[82:83], v200 offset:96
	ds_read_b64 v[72:73], v200 offset:128
	ds_read_b64 v[74:75], v200 offset:160
	ds_read_b64 v[60:61], v200 offset:192
	ds_read_b64 v[62:63], v200 offset:224
	ds_read_b64 v[84:85], v0 offset:256
	ds_read_b64 v[86:87], v0 offset:288
	ds_read_b64 v[76:77], v0 offset:320
	ds_read_b64 v[78:79], v0 offset:352
	ds_read_b64 v[68:69], v0 offset:384
	ds_read_b64 v[70:71], v0 offset:416
	ds_read_b64 v[64:65], v0 offset:448
	ds_read_b64 v[66:67], v0 offset:480
	ds_read_b64 v[100:101], v1 offset:768
	ds_read_b64 v[102:103], v1 offset:800
	v_add_u32_e32 v0, 0x2000, v201
	ds_read_b64 v[96:97], v0 offset:512
	ds_read_b64 v[98:99], v0 offset:544
	ds_read_b64 v[108:109], v0 offset:576
	ds_read_b64 v[110:111], v0 offset:608
	ds_read_b64 v[112:113], v1 offset:832
	ds_read_b64 v[114:115], v1 offset:864
	s_waitcnt lgkmcnt(6)
	v_mfma_f32_16x16x32_bf16 v[100:103], v[100:103], v[84:87], 0
	s_waitcnt lgkmcnt(4)
	v_mfma_f32_16x16x32_bf16 v[104:107], v[96:99], v[88:91], 0
	s_waitcnt lgkmcnt(0)
	v_mfma_f32_16x16x32_bf16 v[100:103], v[112:115], v[76:79], v[100:103]
	ds_read_b64 v[112:113], v0 offset:640
	ds_read_b64 v[114:115], v0 offset:672
	ds_read_b64 v[116:117], v1 offset:896
	ds_read_b64 v[118:119], v1 offset:928
	v_mfma_f32_16x16x32_bf16 v[104:107], v[108:111], v[80:83], v[104:107]
	s_waitcnt lgkmcnt(0)
	v_mfma_f32_16x16x32_bf16 v[100:103], v[116:119], v[68:71], v[100:103]
	ds_read_b64 v[116:117], v0 offset:704
	ds_read_b64 v[118:119], v0 offset:736
	ds_read_b64 v[226:227], v1 offset:960
	ds_read_b64 v[228:229], v1 offset:992
	v_mov_b32_e32 v0, s93
	v_mfma_f32_16x16x32_bf16 v[96:99], v[96:99], v[84:87], 0
	v_mfma_f32_16x16x32_bf16 v[104:107], v[112:115], v[72:75], v[104:107]
	v_mfma_f32_16x16x32_bf16 v[96:99], v[108:111], v[76:79], v[96:99]
	s_waitcnt lgkmcnt(2)
	v_mfma_f32_16x16x32_bf16 v[104:107], v[116:119], v[60:63], v[104:107]
	s_waitcnt lgkmcnt(0)
	v_mfma_f32_16x16x32_bf16 v[100:103], v[226:229], v[64:67], v[100:103]
	v_mov_b32_e32 v226, s93
	s_nop 4
	v_cndmask_b32_e64 v0, v104, v0, s[8:9]
	v_cndmask_b32_e64 v0, v0, v104, s[10:11]
	v_mfma_f32_16x16x32_bf16 v[96:99], v[112:115], v[68:71], v[96:99]
	v_cndmask_b32_e64 v3, v106, 0, s[12:13]
	v_cndmask_b32_e64 v1, v100, v226, s[8:9]
	v_cndmask_b32_e64 v100, v1, v100, s[10:11]
	v_cndmask_b32_e64 v1, 0, v105, s[10:11]
	v_cndmask_b32_e64 v104, v107, 0, s[14:15]
	v_cvt_pk_bf16_f32 v0, v0, v1
	v_cvt_pk_bf16_f32 v1, v3, v104
	ds_read_b128 v[104:107], v202 offset:35328
	ds_read_b128 v[108:111], v202 offset:35392
	v_mfma_f32_16x16x32_bf16 v[96:99], v[116:119], v[64:67], v[96:99]
	v_cndmask_b32_e64 v101, 0, v101, s[10:11]
	v_cndmask_b32_e64 v102, v102, 0, s[12:13]
	v_cndmask_b32_e64 v103, v103, 0, s[14:15]
	v_mov_b32_e32 v3, v2
	s_waitcnt lgkmcnt(0)
	v_pk_mul_f32 v[110:111], v[54:55], v[110:111]
	s_nop 1
	v_cvt_pk_bf16_f32 v96, v96, v97
	v_cvt_pk_bf16_f32 v97, v98, v99
	v_cvt_pk_bf16_f32 v98, v100, v101
	v_cvt_pk_bf16_f32 v99, v102, v103
	v_mfma_f32_16x16x32_bf16 v[100:103], v[92:95], v[0:3], 0
	v_mul_f32_e64 v0, v58, v106
	v_mul_f32_e64 v1, v59, v107
	v_pk_mul_f32 v[106:107], v[52:53], v[108:109]
	v_pk_mul_f32 v[104:105], v[56:57], v[104:105]
	v_cvt_pk_bf16_f32 v106, v106, v107
	v_cvt_pk_bf16_f32 v107, v110, v111
	ds_read_b128 v[108:111], v202 offset:35456
	ds_read_b128 v[112:115], v202 offset:35520
	v_cvt_pk_bf16_f32 v104, v104, v105
	v_cvt_pk_bf16_f32 v105, v0, v1
	v_mfma_f32_16x16x32_bf16 v[96:99], v[92:95], v[96:99], 0
	s_waitcnt lgkmcnt(1)
	v_pk_mul_f32 v[0:1], v[50:51], v[110:111]
	v_pk_mul_f32 v[108:109], v[48:49], v[108:109]
	s_waitcnt lgkmcnt(0)
	v_pk_mul_f32 v[110:111], v[46:47], v[114:115]
	v_pk_mul_f32 v[112:113], v[44:45], v[112:113]
	v_cvt_pk_bf16_f32 v116, v108, v109
	v_cvt_pk_bf16_f32 v118, v112, v113
	v_cvt_pk_bf16_f32 v119, v110, v111
	ds_read_b128 v[108:111], v202 offset:35584
	ds_read_b128 v[112:115], v202 offset:35648
	v_cvt_pk_bf16_f32 v117, v0, v1
	v_mfma_f32_16x16x32_bf16 v[88:91], v[104:107], v[88:91], v[100:103]
	v_cndmask_b32_e64 v3, v222, v190, s[4:5]
	s_waitcnt lgkmcnt(1)
	v_pk_mul_f32 v[0:1], v[42:43], v[110:111]
	s_waitcnt lgkmcnt(0)
	v_pk_mul_f32 v[114:115], v[38:39], v[114:115]
	v_pk_mul_f32 v[110:111], v[36:37], v[112:113]
	v_pk_mul_f32 v[108:109], v[40:41], v[108:109]
	v_cvt_pk_bf16_f32 v110, v110, v111
	v_cvt_pk_bf16_f32 v111, v114, v115
	ds_read_b128 v[112:115], v202 offset:35712
	ds_read_b128 v[226:229], v202 offset:35776
	v_cvt_pk_bf16_f32 v108, v108, v109
	v_cvt_pk_bf16_f32 v109, v0, v1
	v_mfma_f32_16x16x32_bf16 v[84:87], v[104:107], v[84:87], v[96:99]
	s_waitcnt lgkmcnt(1)
	v_pk_mul_f32 v[0:1], v[34:35], v[114:115]
	s_waitcnt lgkmcnt(0)
	v_pk_mul_f32 v[228:229], v[30:31], v[228:229]
	v_pk_mul_f32 v[114:115], v[28:29], v[226:227]
	v_mfma_f32_16x16x32_bf16 v[80:83], v[116:119], v[80:83], v[88:91]
	v_cvt_pk_bf16_f32 v114, v114, v115
	v_cvt_pk_bf16_f32 v115, v228, v229
	ds_read_b128 v[226:229], v202 offset:34816
	ds_read_b64_tr_b16 v[232:233], v198 offset:21760
	ds_read_b64_tr_b16 v[230:231], v198 offset:17408
	ds_read_b64_tr_b16 v[234:235], v198 offset:17440
	v_pk_mul_f32 v[112:113], v[32:33], v[112:113]
	s_waitcnt lgkmcnt(3)
	v_pk_mul_f32 v[58:59], v[58:59], v[228:229]
	v_pk_mul_f32 v[56:57], v[56:57], v[226:227]
	ds_read_b128 v[226:229], v202 offset:34880
	ds_read_b64_tr_b16 v[236:237], v198 offset:21792
	s_waitcnt lgkmcnt(3)
	v_mfma_f32_16x16x32_bf16 v[56:59], v[230:233], v[92:95], v[56:59]
	v_cvt_pk_bf16_f32 v112, v112, v113
	v_cvt_pk_bf16_f32 v113, v0, v1
	s_waitcnt lgkmcnt(1)
	v_pk_mul_f32 v[54:55], v[54:55], v[228:229]
	v_pk_mul_f32 v[52:53], v[52:53], v[226:227]
	ds_read_b128 v[226:229], v202 offset:34944
	ds_read_b64_tr_b16 v[230:231], v198 offset:17472
	ds_read_b64_tr_b16 v[232:233], v198 offset:21824
	v_mfma_f32_16x16x32_bf16 v[76:79], v[116:119], v[76:79], v[84:87]
	v_xor_b32_e32 v1, 0xffffffef, v190
	s_waitcnt lgkmcnt(2)
	v_pk_mul_f32 v[50:51], v[50:51], v[228:229]
	v_pk_mul_f32 v[48:49], v[48:49], v[226:227]
	v_mfma_f32_16x16x32_bf16 v[72:75], v[108:111], v[72:75], v[80:83]
	v_add_u32_e32 v0, 16, v190
	v_add_u32_e32 v1, s74, v1
	s_waitcnt lgkmcnt(0)
	v_mfma_f32_16x16x32_bf16 v[48:51], v[230:233], v[92:95], v[48:51]
	ds_read_b128 v[226:229], v202 offset:35008
	ds_read_b64_tr_b16 v[230:231], v198 offset:17504
	ds_read_b64_tr_b16 v[232:233], v198 offset:21856
	s_waitcnt lgkmcnt(2)
	v_pk_mul_f32 v[46:47], v[46:47], v[228:229]
	v_pk_mul_f32 v[44:45], v[44:45], v[226:227]
	v_mfma_f32_16x16x32_bf16 v[68:71], v[108:111], v[68:71], v[76:79]
	s_waitcnt lgkmcnt(0)
	v_mfma_f32_16x16x32_bf16 v[44:47], v[230:233], v[92:95], v[44:47]
	ds_read_b128 v[226:229], v202 offset:35072
	ds_read_b64_tr_b16 v[230:231], v198 offset:17536
	ds_read_b64_tr_b16 v[232:233], v198 offset:21888
	s_waitcnt lgkmcnt(2)
	v_pk_mul_f32 v[42:43], v[42:43], v[228:229]
	v_pk_mul_f32 v[40:41], v[40:41], v[226:227]
	v_mfma_f32_16x16x32_bf16 v[60:63], v[112:115], v[60:63], v[72:75]
	s_waitcnt lgkmcnt(0)
	v_mfma_f32_16x16x32_bf16 v[40:43], v[230:233], v[92:95], v[40:43]
	ds_read_b128 v[226:229], v202 offset:35136
	ds_read_b64_tr_b16 v[230:231], v198 offset:17568
	ds_read_b64_tr_b16 v[232:233], v198 offset:21920
	s_waitcnt lgkmcnt(2)
	v_pk_mul_f32 v[38:39], v[38:39], v[228:229]
	v_pk_mul_f32 v[36:37], v[36:37], v[226:227]
	v_mfma_f32_16x16x32_bf16 v[64:67], v[112:115], v[64:67], v[68:71]
	s_waitcnt lgkmcnt(0)
	v_mfma_f32_16x16x32_bf16 v[36:39], v[230:233], v[92:95], v[36:39]
	ds_read_b128 v[226:229], v202 offset:35200
	ds_read_b64_tr_b16 v[230:231], v198 offset:17600
	ds_read_b64_tr_b16 v[232:233], v198 offset:21952
	v_cndmask_b32_e64 v68, v1, v0, s[4:5]
	v_cvt_pk_bf16_f32 v1, v62, v63
	s_waitcnt lgkmcnt(2)
	v_pk_mul_f32 v[34:35], v[34:35], v[228:229]
	v_pk_mul_f32 v[32:33], v[32:33], v[226:227]
	v_add_u32_e32 v62, s73, v3
	v_ashrrev_i32_e32 v63, 31, v62
	s_waitcnt lgkmcnt(0)
	v_mfma_f32_16x16x32_bf16 v[32:35], v[230:233], v[92:95], v[32:35]
	ds_read_b128 v[226:229], v202 offset:35264
	ds_read_b64_tr_b16 v[230:231], v198 offset:17632
	ds_read_b64_tr_b16 v[232:233], v198 offset:21984
	v_lshlrev_b64 v[62:63], 11, v[62:63]
	v_cvt_pk_bf16_f32 v0, v60, v61
	s_waitcnt lgkmcnt(2)
	v_pk_mul_f32 v[30:31], v[30:31], v[228:229]
	v_pk_mul_f32 v[28:29], v[28:29], v[226:227]
	v_lshl_add_u64 v[62:63], v[186:187], 0, v[62:63]
	v_mfma_f32_16x16x32_bf16 v[52:55], v[234:237], v[92:95], v[52:55]
	global_store_dwordx2 v[62:63], v[0:1], off
	v_add_u32_e32 v0, s73, v68
	v_ashrrev_i32_e32 v1, 31, v0
	s_waitcnt lgkmcnt(0)
	v_mfma_f32_16x16x32_bf16 v[28:31], v[230:233], v[92:95], v[28:31]
	v_lshlrev_b64 v[0:1], 11, v[0:1]
	v_cvt_pk_bf16_f32 v60, v64, v65
	v_cvt_pk_bf16_f32 v61, v66, v67
	v_lshl_add_u64 v[0:1], v[186:187], 0, v[0:1]
	global_store_dwordx2 v[0:1], v[60:61], off
	s_and_saveexec_b64 s[96:97], vcc
	s_cbranch_execz .LBB0_854
	s_waitcnt vmcnt(8)
	v_cvt_f32_f16_e32 v76, v20
	v_cvt_f32_f16_sdwa v75, v20 dst_sel:DWORD dst_unused:UNUSED_PAD src0_sel:WORD_1
	v_cvt_f32_f16_e32 v74, v21
	v_cvt_f32_f16_sdwa v73, v21 dst_sel:DWORD dst_unused:UNUSED_PAD src0_sel:WORD_1
	v_add_f32_dpp v0, v76, v76 row_shr:1 row_mask:0xf bank_mask:0xf bound_ctrl:1
	v_add_f32_dpp v1, v75, v75 row_shr:1 row_mask:0xf bank_mask:0xf bound_ctrl:1
	v_mov_b32_e32 v62, v2
	v_add_f32_dpp v0, v0, v0 row_shr:2 row_mask:0xf bank_mask:0xf bound_ctrl:1
	v_add_f32_dpp v1, v1, v1 row_shr:2 row_mask:0xf bank_mask:0xf bound_ctrl:1
	v_cvt_f32_f16_e32 v72, v22
	v_add_f32_dpp v0, v0, v0 row_shr:4 row_mask:0xf bank_mask:0xf bound_ctrl:1
	v_add_f32_dpp v20, v74, v74 row_shr:1 row_mask:0xf bank_mask:0xf bound_ctrl:1
	v_add_f32_dpp v1, v1, v1 row_shr:4 row_mask:0xf bank_mask:0xf bound_ctrl:1
	v_add_f32_dpp v0, v0, v0 row_shr:8 row_mask:0xf bank_mask:0xf bound_ctrl:1
	v_add_f32_dpp v20, v20, v20 row_shr:2 row_mask:0xf bank_mask:0xf bound_ctrl:1
	v_add_f32_dpp v1, v1, v1 row_shr:8 row_mask:0xf bank_mask:0xf bound_ctrl:1
	v_mov_b32_dpp v62, v0 row_bcast:15 row_mask:0xa bank_mask:0xf
	v_add_f32_e32 v78, v0, v62
	v_mov_b32_e32 v0, v2
	v_cvt_f32_f16_sdwa v71, v22 dst_sel:DWORD dst_unused:UNUSED_PAD src0_sel:WORD_1
	v_add_f32_dpp v21, v73, v73 row_shr:1 row_mask:0xf bank_mask:0xf bound_ctrl:1
	v_add_f32_dpp v20, v20, v20 row_shr:4 row_mask:0xf bank_mask:0xf bound_ctrl:1
	v_mov_b32_dpp v0, v1 row_bcast:15 row_mask:0xa bank_mask:0xf
	v_add_f32_dpp v21, v21, v21 row_shr:2 row_mask:0xf bank_mask:0xf bound_ctrl:1
	v_add_f32_dpp v20, v20, v20 row_shr:8 row_mask:0xf bank_mask:0xf bound_ctrl:1
	v_add_f32_e32 v79, v1, v0
	v_mov_b32_e32 v0, v2
	v_cvt_f32_f16_e32 v70, v23
	v_add_f32_dpp v22, v72, v72 row_shr:1 row_mask:0xf bank_mask:0xf bound_ctrl:1
	v_add_f32_dpp v21, v21, v21 row_shr:4 row_mask:0xf bank_mask:0xf bound_ctrl:1
	v_mov_b32_dpp v0, v20 row_bcast:15 row_mask:0xa bank_mask:0xf
	v_add_f32_dpp v22, v22, v22 row_shr:2 row_mask:0xf bank_mask:0xf bound_ctrl:1
	v_add_f32_dpp v21, v21, v21 row_shr:8 row_mask:0xf bank_mask:0xf bound_ctrl:1
	v_add_f32_e32 v80, v20, v0
	v_mov_b32_e32 v0, v2
	v_cvt_f32_f16_sdwa v3, v23 dst_sel:DWORD dst_unused:UNUSED_PAD src0_sel:WORD_1
	v_add_f32_dpp v23, v71, v71 row_shr:1 row_mask:0xf bank_mask:0xf bound_ctrl:1
	v_add_f32_dpp v22, v22, v22 row_shr:4 row_mask:0xf bank_mask:0xf bound_ctrl:1
	v_mov_b32_dpp v0, v21 row_bcast:15 row_mask:0xa bank_mask:0xf
	v_add_f32_dpp v23, v23, v23 row_shr:2 row_mask:0xf bank_mask:0xf bound_ctrl:1
	v_add_f32_dpp v22, v22, v22 row_shr:8 row_mask:0xf bank_mask:0xf bound_ctrl:1
	v_add_f32_e32 v81, v21, v0
	v_mov_b32_e32 v0, v2
	v_add_f32_dpp v60, v70, v70 row_shr:1 row_mask:0xf bank_mask:0xf bound_ctrl:1
	v_add_f32_dpp v23, v23, v23 row_shr:4 row_mask:0xf bank_mask:0xf bound_ctrl:1
	v_mov_b32_dpp v0, v22 row_bcast:15 row_mask:0xa bank_mask:0xf
	ds_bpermute_b32 v1, v193, v78
	v_add_f32_dpp v60, v60, v60 row_shr:2 row_mask:0xf bank_mask:0xf bound_ctrl:1
	v_add_f32_dpp v23, v23, v23 row_shr:8 row_mask:0xf bank_mask:0xf bound_ctrl:1
	v_add_f32_e32 v77, v22, v0
	v_mov_b32_e32 v0, v2
	v_add_f32_dpp v60, v60, v60 row_shr:4 row_mask:0xf bank_mask:0xf bound_ctrl:1
	v_add_f32_dpp v61, v3, v3 row_shr:1 row_mask:0xf bank_mask:0xf bound_ctrl:1
	v_mov_b32_dpp v0, v23 row_bcast:15 row_mask:0xa bank_mask:0xf
	v_add_f32_dpp v60, v60, v60 row_shr:8 row_mask:0xf bank_mask:0xf bound_ctrl:1
	v_add_f32_e32 v82, v23, v0
	v_mov_b32_e32 v0, v2
	v_add_f32_dpp v61, v61, v61 row_shr:2 row_mask:0xf bank_mask:0xf bound_ctrl:1
	ds_bpermute_b32 v22, v193, v80
	v_mov_b32_dpp v0, v60 row_bcast:15 row_mask:0xa bank_mask:0xf
	v_add_f32_e32 v83, v60, v0
	s_waitcnt lgkmcnt(1)
	v_sub_f32_e32 v0, v78, v1
	ds_bpermute_b32 v1, v193, v79
	v_med3_f32 v0, v0, s69, v189
	v_add_f32_dpp v61, v61, v61 row_shr:4 row_mask:0xf bank_mask:0xf bound_ctrl:1
	v_mul_f32_e32 v0, 0x3fb8aa3b, v0
	v_exp_f32_e32 v20, v0
	v_add_f32_dpp v61, v61, v61 row_shr:8 row_mask:0xf bank_mask:0xf bound_ctrl:1
	v_mov_b32_e32 v0, v2
	s_waitcnt lgkmcnt(0)
	v_sub_f32_e32 v1, v79, v1
	v_med3_f32 v1, v1, s69, v189
	v_mov_b32_dpp v0, v61 row_bcast:15 row_mask:0xa bank_mask:0xf
	v_add_f32_e32 v84, v61, v0
	v_mul_f32_e32 v1, 0x3fb8aa3b, v1
	v_exp_f32_e32 v21, v1
	ds_bpermute_b32 v1, v193, v81
	ds_bpermute_b32 v62, v193, v77
	ds_bpermute_b32 v63, v193, v82
	ds_bpermute_b32 v64, v193, v83
	ds_bpermute_b32 v65, v193, v84
	v_sub_f32_e32 v22, v80, v22
	s_waitcnt lgkmcnt(4)
	v_sub_f32_e32 v1, v81, v1
	s_waitcnt lgkmcnt(3)
	v_sub_f32_e32 v62, v77, v62
	s_waitcnt lgkmcnt(2)
	v_sub_f32_e32 v63, v82, v63
	s_waitcnt lgkmcnt(1)
	v_sub_f32_e32 v64, v83, v64
	s_waitcnt lgkmcnt(0)
	v_sub_f32_e32 v65, v84, v65
	v_med3_f32 v22, v22, s69, v189
	v_med3_f32 v1, v1, s69, v189
	v_med3_f32 v62, v62, s69, v189
	v_med3_f32 v63, v63, s69, v189
	v_med3_f32 v64, v64, s69, v189
	v_med3_f32 v65, v65, s69, v189
	v_mul_f32_e32 v22, 0x3fb8aa3b, v22
	v_mul_f32_e32 v1, 0x3fb8aa3b, v1
	v_mul_f32_e32 v62, 0x3fb8aa3b, v62
	v_mul_f32_e32 v63, 0x3fb8aa3b, v63
	v_mul_f32_e32 v64, 0x3fb8aa3b, v64
	v_mul_f32_e32 v65, 0x3fb8aa3b, v65
	v_exp_f32_e32 v60, v22
	v_exp_f32_e32 v61, v1
	v_exp_f32_e32 v62, v62
	v_exp_f32_e32 v63, v63
	v_exp_f32_e32 v64, v64
	v_exp_f32_e32 v65, v65
	ds_bpermute_b32 v0, v194, v20
	ds_bpermute_b32 v1, v194, v21
	ds_bpermute_b32 v22, v194, v60
	ds_bpermute_b32 v23, v194, v61
	ds_bpermute_b32 v68, v194, v62
	ds_bpermute_b32 v69, v194, v63
	ds_bpermute_b32 v66, v194, v64
	ds_bpermute_b32 v67, v194, v65
	s_and_saveexec_b64 s[16:17], s[6:7]
	s_cbranch_execz .LBB0_853
	v_mul_f32_e32 v78, 0x3fb8aa3b, v78
	v_mul_f32_e32 v79, 0x3fb8aa3b, v79
	v_mul_f32_e32 v80, 0x3fb8aa3b, v80
	v_mul_f32_e32 v81, 0x3fb8aa3b, v81
	v_exp_f32_e32 v78, v78
	v_exp_f32_e32 v79, v79
	v_exp_f32_e32 v80, v80
	v_exp_f32_e32 v81, v81
	v_mul_f32_e32 v77, 0x3fb8aa3b, v77
	ds_write_b128 v203, v[78:81]
	v_exp_f32_e32 v78, v77
	v_mul_f32_e32 v77, 0x3fb8aa3b, v82
	v_exp_f32_e32 v79, v77
	v_mul_f32_e32 v77, 0x3fb8aa3b, v83
	v_exp_f32_e32 v80, v77
	v_mul_f32_e32 v77, 0x3fb8aa3b, v84
	v_exp_f32_e32 v81, v77
	ds_write_b128 v203, v[78:81] offset:16
	s_branch .LBB0_853

.LBB0_879:
	s_andn2_b64 vcc, exec, s[82:83]
	s_cbranch_vccnz .LBB0_816
	s_lshl_b64 s[6:7], s[56:57], 16
	s_add_u32 s3, s40, s6
	s_addc_u32 s8, s41, s7
	s_lshl_b64 s[6:7], s[92:93], 15
	s_add_u32 s14, s3, s6
	s_addc_u32 s15, s8, s7
	s_and_b64 s[6:7], s[4:5], exec
	s_mov_b32 s3, 0xed32000
	s_cselect_b32 s3, s3, 0xf532000
	s_add_u32 s3, s24, s3
	s_addc_u32 s6, s25, 0
	s_add_u32 s3, s3, 0xff000000
	s_addc_u32 s6, s6, -1
	s_cmp_eq_u32 s92, 0
	s_cselect_b32 s12, s76, s6
	s_cselect_b32 s3, s28, s3
	s_lshl_b32 s13, s59, 8
	s_add_u32 s6, s60, s13
	s_addc_u32 s7, s61, 0
	s_lshl_b32 s10, s92, 7
	s_add_u32 s6, s6, s10
	s_addc_u32 s7, s7, 0
	v_readlane_b32 s8, v254, 40
	s_add_u32 s8, s8, s13
	v_readlane_b32 s9, v254, 41
	s_addc_u32 s9, s9, 0
	s_lshl_b32 s11, s58, 10
	s_add_u32 s11, s84, s11
	s_addc_u32 s16, s85, 0
	s_add_u32 s11, s11, s13
	s_addc_u32 s16, s16, 0
	s_add_u32 s10, s11, s10
	s_addc_u32 s11, s16, 0
	s_add_u32 s56, s3, s13
	v_mov_b32_e32 v1, v224
	s_addc_u32 s57, s12, 0
	s_lshr_b32 s3, s74, 5
	v_ashrrev_i32_e32 v3, 6, v1
	v_and_b32_e32 v88, 15, v1
	v_lshlrev_b32_e32 v0, 4, v3
	s_and_b64 s[12:13], s[94:95], exec
	s_waitcnt vmcnt(7)
	v_lshrrev_b32_e32 v10, 2, v1
	s_cselect_b32 s12, 0, s15
	s_cselect_b32 s13, 0, s14
	s_waitcnt vmcnt(2)
	v_or_b32_e32 v6, v0, v88
	v_mov_b32_e32 v4, s13
	v_mov_b32_e32 v5, s12
	v_ashrrev_i32_e32 v7, 31, v6
	v_and_b32_e32 v48, 12, v10
	v_lshl_add_u64 v[4:5], v[6:7], 2, v[4:5]
	v_lshlrev_b32_e32 v6, 9, v48
	v_mov_b32_e32 v7, v2
	v_lshl_add_u64 v[4:5], v[4:5], 0, v[6:7]
	s_movk_i32 s12, 0x6000
	v_add_co_u32_e32 v6, vcc, s12, v4
	s_movk_i32 s12, 0x4000
	s_nop 0
	v_addc_co_u32_e32 v7, vcc, 0, v5, vcc
	global_load_dword v28, v[6:7], off
	global_load_dword v29, v[6:7], off offset:512
	global_load_dword v30, v[6:7], off offset:1024
	global_load_dword v31, v[6:7], off offset:1536
	v_add_co_u32_e32 v6, vcc, s12, v4
	s_movk_i32 s12, 0x2000
	s_nop 0
	v_addc_co_u32_e32 v7, vcc, 0, v5, vcc
	v_add_co_u32_e32 v8, vcc, s12, v4
	v_ashrrev_i32_e32 v90, 4, v1
	s_nop 0
	v_addc_co_u32_e32 v9, vcc, 0, v5, vcc
	global_load_dword v36, v[6:7], off
	global_load_dword v37, v[6:7], off offset:512
	global_load_dword v38, v[6:7], off offset:1024
	global_load_dword v39, v[6:7], off offset:1536
	global_load_dword v40, v[8:9], off
	global_load_dword v41, v[8:9], off offset:512
	global_load_dword v42, v[8:9], off offset:1024
	global_load_dword v43, v[8:9], off offset:1536
	global_load_dword v49, v[4:5], off
	global_load_dword v50, v[4:5], off offset:512
	global_load_dword v51, v[4:5], off offset:1024
	global_load_dword v52, v[4:5], off offset:1536
	v_and_b32_e32 v4, 8, v10
	v_and_or_b32 v53, v0, 48, v4
	v_lshlrev_b32_e32 v4, 4, v1
	v_sub_u32_e32 v5, s74, v90
	v_and_b32_e32 v46, 0xf0, v4
	v_add_u32_e32 v4, 32, v90
	v_subrev_u32_e32 v5, 33, v5
	v_cndmask_b32_e64 v4, v5, v4, s[4:5]
	v_add_u32_e32 v4, s73, v4
	v_mov_b64_e32 v[8:9], s[8:9]
	v_mad_i64_i32 v[4:5], s[12:13], v4, s89, v[8:9]
	s_movk_i32 s12, 0xffdf
	v_and_b32_e32 v89, 31, v1
	v_bitop3_b32 v7, v1, s12, 31 bitop3:0x6c
	v_or_b32_e32 v6, 32, v89
	v_add_u32_e32 v7, s74, v7
	v_cndmask_b32_e64 v6, v7, v6, s[4:5]
	v_add_u32_e32 v10, s73, v6
	v_ashrrev_i32_e32 v11, 31, v10
	v_lshlrev_b64 v[6:7], 11, v[10:11]
	v_lshlrev_b32_e32 v44, 1, v53
	v_mov_b32_e32 v45, v2
	v_mov_b32_e32 v47, v2
	v_lshl_add_u64 v[6:7], s[10:11], 0, v[6:7]
	v_xad_u32 v18, v89, -1, s74
	v_lshl_add_u64 v[4:5], v[4:5], 0, v[46:47]
	v_lshl_add_u64 v[12:13], v[6:7], 0, v[44:45]
	v_cndmask_b32_e64 v18, v18, v89, s[4:5]
	global_load_dwordx4 v[4:7], v[4:5], off
	s_nop 0
	global_load_dwordx4 v[20:23], v[12:13], off
	v_xad_u32 v12, v90, -1, s74
	v_add_u32_e32 v18, s73, v18
	v_cndmask_b32_e64 v12, v12, v90, s[4:5]
	v_ashrrev_i32_e32 v19, 31, v18
	v_mov_b64_e32 v[16:17], s[6:7]
	v_add_u32_e32 v12, s73, v12
	v_lshlrev_b64 v[24:25], 11, v[18:19]
	v_mad_i64_i32 v[10:11], s[12:13], v10, s89, v[16:17]
	v_mad_i64_i32 v[8:9], s[12:13], v12, s89, v[8:9]
	v_lshl_add_u64 v[24:25], s[10:11], 0, v[24:25]
	v_mad_i64_i32 v[16:17], s[12:13], v18, s89, v[16:17]
	v_lshl_add_u64 v[10:11], v[10:11], 0, v[44:45]
	v_lshl_add_u64 v[8:9], v[8:9], 0, v[46:47]
	v_lshl_add_u64 v[24:25], v[24:25], 0, v[44:45]
	v_lshl_add_u64 v[16:17], v[16:17], 0, v[44:45]
	global_load_dwordx4 v[12:15], v[10:11], off
	s_nop 0
	global_load_dwordx4 v[8:11], v[8:9], off
	s_nop 0
	global_load_dwordx4 v[24:27], v[24:25], off
	s_nop 0
	global_load_dwordx4 v[16:19], v[16:17], off
	v_lshlrev_b32_e32 v54, 3, v1
	v_lshl_add_u64 v[80:81], s[6:7], 0, v[44:45]
	s_movk_i32 s6, 0xfc
	v_lshl_add_u64 v[82:83], s[10:11], 0, v[44:45]
	v_add_u32_e32 v45, 0, v44
	v_lshl_add_u64 v[84:85], s[8:9], 0, v[46:47]
	s_movk_i32 s8, 0x110
	v_cmp_gt_i32_e32 vcc, 4, v3
	v_lshlrev_b32_e32 v3, 5, v3
	v_lshlrev_b32_e32 v47, 2, v53
	s_mov_b32 s28, 3
	s_add_i32 s35, s3, -1
	v_cmp_lt_u32_e64 s[10:11], v48, v88
	v_xad_u32 v111, v88, -1, s74
	s_waitcnt vmcnt(21)
	v_cndmask_b32_e64 v32, v28, 0, s[94:95]
	s_waitcnt vmcnt(20)
	v_cndmask_b32_e64 v33, v29, 0, s[94:95]
	s_waitcnt vmcnt(19)
	v_cndmask_b32_e64 v34, v30, 0, s[94:95]
	s_waitcnt vmcnt(17)
	v_cndmask_b32_e64 v28, v36, 0, s[94:95]
	s_waitcnt vmcnt(16)
	v_cndmask_b32_e64 v29, v37, 0, s[94:95]
	v_cndmask_b32_e64 v35, v31, 0, s[94:95]
	s_waitcnt vmcnt(15)
	v_cndmask_b32_e64 v30, v38, 0, s[94:95]
	s_waitcnt vmcnt(13)
	v_cndmask_b32_e64 v36, v40, 0, s[94:95]
	s_waitcnt vmcnt(12)
	v_cndmask_b32_e64 v37, v41, 0, s[94:95]
	v_cndmask_b32_e64 v31, v39, 0, s[94:95]
	s_waitcnt vmcnt(11)
	v_cndmask_b32_e64 v38, v42, 0, s[94:95]
	s_waitcnt vmcnt(9)
	v_cndmask_b32_e64 v40, v49, 0, s[94:95]
	v_lshlrev_b32_e32 v49, 2, v1
	v_and_or_b32 v91, v49, s71, 60
	v_bitop3_b32 v92, v49, s6, v188 bitop3:0xc8
	v_bitop3_b32 v49, v54, s71, v54 bitop3:0xc
	v_lshlrev_b32_e32 v49, 2, v49
	v_add3_u32 v93, v45, v44, v49
	v_mul_u32_u24_e32 v44, 0x48, v89
	v_lshl_add_u32 v94, v44, 1, v45
	v_bfe_u32 v45, v1, 2, 4
	v_mul_lo_u32 v44, v90, s8
	v_mul_u32_u24_e32 v1, 0x88, v45
	v_add3_u32 v95, 0, v46, v44
	v_lshl_add_u32 v44, v1, 1, 0
	v_and_b32_e32 v46, 24, v54
	s_waitcnt vmcnt(8)
	v_cndmask_b32_e64 v41, v50, 0, s[94:95]
	v_add3_u32 v96, v44, v3, v46
	v_lshlrev_b32_e32 v44, 1, v48
	v_mul_u32_u24_e32 v50, 0x48, v88
	v_ashrrev_i32_e32 v1, 31, v0
	v_add_u32_e32 v3, 0, v44
	v_lshlrev_b32_e32 v50, 1, v50
	v_add_u32_e32 v97, v3, v50
	v_add3_u32 v98, 0, v50, v44
	v_or_b32_e32 v50, 2, v48
	v_add_u32_e32 v99, v3, v44
	v_mul_u32_u24_e32 v3, 0x48, v45
	v_lshl_add_u64 v[0:1], v[0:1], 1, s[56:57]
	v_mov_b32_e32 v45, v2
	v_cmp_gt_u32_e64 s[12:13], v50, v88
	v_or_b32_e32 v50, 3, v48
	v_lshlrev_b32_e32 v3, 1, v3
	v_lshl_add_u64 v[86:87], v[0:1], 0, v[44:45]
	v_lshlrev_b32_e32 v0, 2, v48
	v_cndmask_b32_e64 v39, v43, 0, s[94:95]
	s_waitcnt vmcnt(7)
	v_cndmask_b32_e64 v42, v51, 0, s[94:95]
	s_waitcnt vmcnt(6)
	v_cndmask_b32_e64 v43, v52, 0, s[94:95]
	v_cmp_eq_u32_e64 s[6:7], 15, v88
	v_cmp_gt_u32_e64 s[8:9], v48, v88
	v_cmp_gt_u32_e64 s[14:15], v50, v88
	v_add3_u32 v100, 0, v3, v46
	v_add3_u32 v101, s88, v47, v49
	v_add_u32_e32 v102, 0xf200, v96
	v_add_u32_e32 v103, s72, v0
	v_add_u32_e32 v104, s75, v0
	v_add_u32_e32 v105, s18, v0
	v_add_u32_e32 v106, s19, v0
	v_add_u32_e32 v107, s88, v0
	v_add_u32_e32 v108, s70, v0
	v_add_u32_e32 v109, s29, v0
	v_add_u32_e32 v110, s68, v0
	s_waitcnt vmcnt(0)
	s_branch .LBB0_883

.LBB0_882:
	s_or_b64 exec, exec, s[56:57]
	s_min_i32 s16, s28, s35
	s_lshl_b32 s16, s16, 5
	v_or_b32_e32 v0, s16, v89
	v_xad_u32 v1, v0, -1, s74
	v_cndmask_b32_e64 v0, v1, v0, s[4:5]
	v_add_u32_e32 v1, s16, v90
	v_xad_u32 v3, v1, -1, s74
	v_add_u32_e32 v0, s73, v0
	v_cndmask_b32_e64 v3, v3, v1, s[4:5]
	v_ashrrev_i32_e32 v1, 31, v0
	s_waitcnt vmcnt(7)
	ds_write_b128 v95, v[4:7] offset:61952
	v_mad_i64_i32 v[4:5], s[16:17], v0, s89, v[80:81]
	v_lshlrev_b64 v[0:1], 11, v[0:1]
	v_lshl_add_u64 v[0:1], v[82:83], 0, v[0:1]
	global_load_dwordx4 v[12:15], v[4:5], off
	global_load_dwordx4 v[20:23], v[0:1], off
	v_add_u32_e32 v0, s73, v3
	v_mad_i64_i32 v[0:1], s[16:17], v0, s89, v[84:85]
	global_load_dwordx4 v[4:7], v[0:1], off
	v_add_u32_e32 v0, 0x8800, v97
	s_waitcnt lgkmcnt(0)
	s_barrier
	ds_read_b64_tr_b16 v[60:61], v102
	ds_read_b64_tr_b16 v[62:63], v102 offset:4352
	ds_read_b64 v[56:57], v0 offset:1024
	ds_read_b64 v[58:59], v0 offset:1056
	ds_read_b64 v[44:45], v0 offset:1088
	ds_read_b64 v[46:47], v0 offset:1120
	v_add_u32_e32 v0, 0x9000, v97
	ds_read_b64 v[52:53], v0 offset:1280
	ds_read_b64 v[54:55], v0 offset:1312
	ds_read_b64 v[48:49], v0 offset:1344
	ds_read_b64 v[50:51], v0 offset:1376
	v_add_u32_e32 v0, 0xa800, v98
	v_add_u32_e32 v1, 0xb000, v98
	ds_read_b64 v[64:65], v0 offset:1536
	ds_read_b64 v[66:67], v0 offset:1568
	ds_read_b64 v[68:69], v1 offset:1792
	ds_read_b64 v[70:71], v1 offset:1824
	ds_read_b64 v[76:77], v0 offset:1600
	ds_read_b64 v[78:79], v0 offset:1632
	ds_read_b64 v[112:113], v1 offset:1856
	ds_read_b64 v[114:115], v1 offset:1888
	s_waitcnt lgkmcnt(6)
	v_mfma_f32_16x16x32_bf16 v[72:75], v[64:67], v[56:59], 0
	v_mov_b32_e32 v0, s93
	s_add_i32 s28, s28, 2
	v_subrev_u32_e32 v111, 64, v111
	s_waitcnt lgkmcnt(4)
	v_mfma_f32_16x16x32_bf16 v[68:71], v[68:71], v[52:55], 0
	s_cmp_lt_u32 s58, s3
	s_waitcnt lgkmcnt(2)
	v_mfma_f32_16x16x32_bf16 v[72:75], v[76:79], v[44:47], v[72:75]
	s_waitcnt lgkmcnt(0)
	v_mfma_f32_16x16x32_bf16 v[68:71], v[112:115], v[48:51], v[68:71]
	v_mov_b32_e32 v112, s93
	s_nop 4
	v_cndmask_b32_e64 v0, v72, v0, s[8:9]
	v_cndmask_b32_e64 v0, v0, v72, s[10:11]
	v_mfma_f32_16x16x32_bf16 v[64:67], v[64:67], v[52:55], 0
	v_cndmask_b32_e64 v3, v74, 0, s[12:13]
	v_cndmask_b32_e64 v1, v68, v112, s[8:9]
	v_cndmask_b32_e64 v68, v1, v68, s[10:11]
	v_cndmask_b32_e64 v1, 0, v73, s[10:11]
	v_cndmask_b32_e64 v72, v75, 0, s[14:15]
	v_mfma_f32_16x16x32_bf16 v[64:67], v[76:79], v[48:51], v[64:67]
	v_cvt_pk_bf16_f32 v0, v0, v1
	v_cvt_pk_bf16_f32 v1, v3, v72
	ds_read_b128 v[72:75], v103
	ds_read_b128 v[76:79], v104
	v_cndmask_b32_e64 v69, 0, v69, s[10:11]
	v_cndmask_b32_e64 v70, v70, 0, s[12:13]
	v_cndmask_b32_e64 v71, v71, 0, s[14:15]
	v_mov_b32_e32 v3, v2
	v_cvt_pk_bf16_f32 v64, v64, v65
	v_cvt_pk_bf16_f32 v65, v66, v67
	v_cvt_pk_bf16_f32 v66, v68, v69
	v_cvt_pk_bf16_f32 v67, v70, v71
	v_mfma_f32_16x16x32_bf16 v[68:71], v[60:63], v[0:3], 0
	s_waitcnt lgkmcnt(1)
	v_pk_mul_f32 v[0:1], v[42:43], v[74:75]
	s_waitcnt lgkmcnt(0)
	v_pk_mul_f32 v[78:79], v[38:39], v[78:79]
	v_pk_mul_f32 v[74:75], v[36:37], v[76:77]
	v_pk_mul_f32 v[72:73], v[40:41], v[72:73]
	v_cvt_pk_bf16_f32 v74, v74, v75
	v_cvt_pk_bf16_f32 v75, v78, v79
	ds_read_b128 v[76:79], v105
	ds_read_b128 v[112:115], v106
	v_cvt_pk_bf16_f32 v72, v72, v73
	v_cvt_pk_bf16_f32 v73, v0, v1
	v_mfma_f32_16x16x32_bf16 v[64:67], v[60:63], v[64:67], 0
	s_waitcnt lgkmcnt(1)
	v_pk_mul_f32 v[0:1], v[30:31], v[78:79]
	s_waitcnt lgkmcnt(0)
	v_pk_mul_f32 v[114:115], v[34:35], v[114:115]
	v_pk_mul_f32 v[78:79], v[32:33], v[112:113]
	v_pk_mul_f32 v[76:77], v[28:29], v[76:77]
	v_cvt_pk_bf16_f32 v78, v78, v79
	v_cvt_pk_bf16_f32 v79, v114, v115
	ds_read_b128 v[112:115], v107
	ds_read_b64_tr_b16 v[118:119], v100 offset:55552
	ds_read_b64_tr_b16 v[116:117], v100 offset:53248
	ds_read_b64_tr_b16 v[120:121], v100 offset:53280
	v_cvt_pk_bf16_f32 v76, v76, v77
	s_waitcnt lgkmcnt(3)
	v_pk_mul_f32 v[42:43], v[42:43], v[114:115]
	v_pk_mul_f32 v[40:41], v[40:41], v[112:113]
	ds_read_b128 v[112:115], v108
	ds_read_b64_tr_b16 v[122:123], v100 offset:55584
	v_cvt_pk_bf16_f32 v77, v0, v1
	v_mfma_f32_16x16x32_bf16 v[56:59], v[72:75], v[56:59], v[68:71]
	v_xor_b32_e32 v3, 0xffffffdf, v88
	s_waitcnt lgkmcnt(1)
	v_pk_mul_f32 v[38:39], v[38:39], v[114:115]
	v_pk_mul_f32 v[36:37], v[36:37], v[112:113]
	v_mfma_f32_16x16x32_bf16 v[40:43], v[116:119], v[60:63], v[40:43]
	ds_read_b128 v[112:115], v109
	ds_read_b64_tr_b16 v[116:117], v100 offset:53312
	ds_read_b64_tr_b16 v[118:119], v100 offset:55616
	v_add_u32_e32 v0, 32, v88
	v_add_u32_e32 v3, s74, v3
	v_mfma_f32_16x16x32_bf16 v[52:55], v[72:75], v[52:55], v[64:67]
	s_waitcnt lgkmcnt(2)
	v_pk_mul_f32 v[30:31], v[30:31], v[114:115]
	v_pk_mul_f32 v[28:29], v[28:29], v[112:113]
	v_cndmask_b32_e64 v3, v3, v0, s[4:5]
	v_mfma_f32_16x16x32_bf16 v[44:47], v[76:79], v[44:47], v[56:59]
	v_xor_b32_e32 v0, 0xffffffcf, v88
	v_add_u32_e32 v1, 48, v88
	v_add_u32_e32 v0, s74, v0
	s_waitcnt lgkmcnt(0)
	v_mfma_f32_16x16x32_bf16 v[28:31], v[116:119], v[60:63], v[28:31]
	ds_read_b128 v[112:115], v110
	ds_read_b64_tr_b16 v[116:117], v100 offset:53344
	ds_read_b64_tr_b16 v[118:119], v100 offset:55648
	v_add_u32_e32 v88, 64, v88
	s_waitcnt lgkmcnt(2)
	v_pk_mul_f32 v[34:35], v[34:35], v[114:115]
	v_mfma_f32_16x16x32_bf16 v[48:51], v[76:79], v[48:51], v[52:55]
	v_mul_f32_e64 v32, v32, v112
	v_mul_f32_e64 v33, v33, v113
	s_nop 0
	v_cndmask_b32_e64 v52, v0, v1, s[4:5]
	v_cvt_pk_bf16_f32 v1, v46, v47
	v_add_u32_e32 v46, s73, v3
	v_ashrrev_i32_e32 v47, 31, v46
	v_lshlrev_b64 v[46:47], 11, v[46:47]
	v_cvt_pk_bf16_f32 v0, v44, v45
	v_lshl_add_u64 v[46:47], v[86:87], 0, v[46:47]
	v_mfma_f32_16x16x32_bf16 v[36:39], v[120:123], v[60:63], v[36:39]
	global_store_dwordx2 v[46:47], v[0:1], off
	v_add_u32_e32 v0, s73, v52
	v_ashrrev_i32_e32 v1, 31, v0
	s_waitcnt lgkmcnt(0)
	v_mfma_f32_16x16x32_bf16 v[32:35], v[116:119], v[60:63], v[32:35]
	v_lshlrev_b64 v[0:1], 11, v[0:1]
	v_cvt_pk_bf16_f32 v44, v48, v49
	v_cvt_pk_bf16_f32 v45, v50, v51
	v_lshl_add_u64 v[0:1], v[86:87], 0, v[0:1]
	global_store_dwordx2 v[0:1], v[44:45], off
	s_cbranch_scc0 .LBB0_815
.LBB0_883:
	s_and_saveexec_b64 s[56:57], vcc
	s_cbranch_execz .LBB0_887
	s_waitcnt vmcnt(8)
	v_cvt_f32_f16_e32 v60, v24
	v_cvt_f32_f16_sdwa v59, v24 dst_sel:DWORD dst_unused:UNUSED_PAD src0_sel:WORD_1
	v_cvt_f32_f16_e32 v58, v25
	v_cvt_f32_f16_sdwa v57, v25 dst_sel:DWORD dst_unused:UNUSED_PAD src0_sel:WORD_1
	v_add_f32_dpp v0, v60, v60 row_shr:1 row_mask:0xf bank_mask:0xf bound_ctrl:1
	v_add_f32_dpp v1, v59, v59 row_shr:1 row_mask:0xf bank_mask:0xf bound_ctrl:1
	v_mov_b32_e32 v46, 0
	v_add_f32_dpp v0, v0, v0 row_shr:2 row_mask:0xf bank_mask:0xf bound_ctrl:1
	v_add_f32_dpp v1, v1, v1 row_shr:2 row_mask:0xf bank_mask:0xf bound_ctrl:1
	v_cvt_f32_f16_e32 v56, v26
	v_add_f32_dpp v0, v0, v0 row_shr:4 row_mask:0xf bank_mask:0xf bound_ctrl:1
	v_add_f32_dpp v24, v58, v58 row_shr:1 row_mask:0xf bank_mask:0xf bound_ctrl:1
	v_add_f32_dpp v1, v1, v1 row_shr:4 row_mask:0xf bank_mask:0xf bound_ctrl:1
	v_add_f32_dpp v0, v0, v0 row_shr:8 row_mask:0xf bank_mask:0xf bound_ctrl:1
	v_add_f32_dpp v24, v24, v24 row_shr:2 row_mask:0xf bank_mask:0xf bound_ctrl:1
	v_add_f32_dpp v1, v1, v1 row_shr:8 row_mask:0xf bank_mask:0xf bound_ctrl:1
	v_mov_b32_dpp v46, v0 row_bcast:15 row_mask:0xa bank_mask:0xf
	v_add_f32_e32 v62, v0, v46
	v_mov_b32_e32 v0, 0
	v_cvt_f32_f16_sdwa v55, v26 dst_sel:DWORD dst_unused:UNUSED_PAD src0_sel:WORD_1
	v_add_f32_dpp v25, v57, v57 row_shr:1 row_mask:0xf bank_mask:0xf bound_ctrl:1
	v_add_f32_dpp v24, v24, v24 row_shr:4 row_mask:0xf bank_mask:0xf bound_ctrl:1
	v_mov_b32_dpp v0, v1 row_bcast:15 row_mask:0xa bank_mask:0xf
	v_add_f32_dpp v25, v25, v25 row_shr:2 row_mask:0xf bank_mask:0xf bound_ctrl:1
	v_add_f32_dpp v24, v24, v24 row_shr:8 row_mask:0xf bank_mask:0xf bound_ctrl:1
	v_add_f32_e32 v63, v1, v0
	v_mov_b32_e32 v0, 0
	v_cvt_f32_f16_e32 v54, v27
	v_add_f32_dpp v26, v56, v56 row_shr:1 row_mask:0xf bank_mask:0xf bound_ctrl:1
	v_add_f32_dpp v25, v25, v25 row_shr:4 row_mask:0xf bank_mask:0xf bound_ctrl:1
	v_mov_b32_dpp v0, v24 row_bcast:15 row_mask:0xa bank_mask:0xf
	v_add_f32_dpp v26, v26, v26 row_shr:2 row_mask:0xf bank_mask:0xf bound_ctrl:1
	v_add_f32_dpp v25, v25, v25 row_shr:8 row_mask:0xf bank_mask:0xf bound_ctrl:1
	v_add_f32_e32 v64, v24, v0
	v_mov_b32_e32 v0, 0
	v_cvt_f32_f16_sdwa v3, v27 dst_sel:DWORD dst_unused:UNUSED_PAD src0_sel:WORD_1
	v_add_f32_dpp v27, v55, v55 row_shr:1 row_mask:0xf bank_mask:0xf bound_ctrl:1
	v_add_f32_dpp v26, v26, v26 row_shr:4 row_mask:0xf bank_mask:0xf bound_ctrl:1
	v_mov_b32_dpp v0, v25 row_bcast:15 row_mask:0xa bank_mask:0xf
	v_add_f32_dpp v27, v27, v27 row_shr:2 row_mask:0xf bank_mask:0xf bound_ctrl:1
	v_add_f32_dpp v26, v26, v26 row_shr:8 row_mask:0xf bank_mask:0xf bound_ctrl:1
	v_add_f32_e32 v65, v25, v0
	v_mov_b32_e32 v0, 0
	v_add_f32_dpp v44, v54, v54 row_shr:1 row_mask:0xf bank_mask:0xf bound_ctrl:1
	v_add_f32_dpp v27, v27, v27 row_shr:4 row_mask:0xf bank_mask:0xf bound_ctrl:1
	v_mov_b32_dpp v0, v26 row_bcast:15 row_mask:0xa bank_mask:0xf
	ds_bpermute_b32 v1, v91, v62
	v_add_f32_dpp v44, v44, v44 row_shr:2 row_mask:0xf bank_mask:0xf bound_ctrl:1
	v_add_f32_dpp v27, v27, v27 row_shr:8 row_mask:0xf bank_mask:0xf bound_ctrl:1
	v_add_f32_e32 v61, v26, v0
	v_mov_b32_e32 v0, 0
	v_add_f32_dpp v44, v44, v44 row_shr:4 row_mask:0xf bank_mask:0xf bound_ctrl:1
	v_add_f32_dpp v45, v3, v3 row_shr:1 row_mask:0xf bank_mask:0xf bound_ctrl:1
	v_mov_b32_dpp v0, v27 row_bcast:15 row_mask:0xa bank_mask:0xf
	v_add_f32_dpp v44, v44, v44 row_shr:8 row_mask:0xf bank_mask:0xf bound_ctrl:1
	v_add_f32_e32 v66, v27, v0
	v_mov_b32_e32 v0, 0
	v_add_f32_dpp v45, v45, v45 row_shr:2 row_mask:0xf bank_mask:0xf bound_ctrl:1
	ds_bpermute_b32 v26, v91, v64
	v_mov_b32_dpp v0, v44 row_bcast:15 row_mask:0xa bank_mask:0xf
	v_add_f32_e32 v67, v44, v0
	s_waitcnt lgkmcnt(1)
	v_sub_f32_e32 v0, v62, v1
	ds_bpermute_b32 v1, v91, v63
	v_med3_f32 v0, v0, s69, v189
	v_add_f32_dpp v45, v45, v45 row_shr:4 row_mask:0xf bank_mask:0xf bound_ctrl:1
	v_mul_f32_e32 v0, 0x3fb8aa3b, v0
	v_exp_f32_e32 v24, v0
	v_add_f32_dpp v45, v45, v45 row_shr:8 row_mask:0xf bank_mask:0xf bound_ctrl:1
	v_mov_b32_e32 v0, 0
	s_waitcnt lgkmcnt(0)
	v_sub_f32_e32 v1, v63, v1
	v_med3_f32 v1, v1, s69, v189
	v_mov_b32_dpp v0, v45 row_bcast:15 row_mask:0xa bank_mask:0xf
	v_add_f32_e32 v68, v45, v0
	v_mul_f32_e32 v1, 0x3fb8aa3b, v1
	v_exp_f32_e32 v25, v1
	ds_bpermute_b32 v1, v91, v65
	ds_bpermute_b32 v46, v91, v61
	ds_bpermute_b32 v47, v91, v66
	ds_bpermute_b32 v48, v91, v67
	ds_bpermute_b32 v49, v91, v68
	v_sub_f32_e32 v26, v64, v26
	s_waitcnt lgkmcnt(4)
	v_sub_f32_e32 v1, v65, v1
	s_waitcnt lgkmcnt(3)
	v_sub_f32_e32 v46, v61, v46
	s_waitcnt lgkmcnt(2)
	v_sub_f32_e32 v47, v66, v47
	s_waitcnt lgkmcnt(1)
	v_sub_f32_e32 v48, v67, v48
	s_waitcnt lgkmcnt(0)
	v_sub_f32_e32 v49, v68, v49
	v_med3_f32 v26, v26, s69, v189
	v_med3_f32 v1, v1, s69, v189
	v_med3_f32 v46, v46, s69, v189
	v_med3_f32 v47, v47, s69, v189
	v_med3_f32 v48, v48, s69, v189
	v_med3_f32 v49, v49, s69, v189
	v_mul_f32_e32 v26, 0x3fb8aa3b, v26
	v_mul_f32_e32 v1, 0x3fb8aa3b, v1
	v_mul_f32_e32 v46, 0x3fb8aa3b, v46
	v_mul_f32_e32 v47, 0x3fb8aa3b, v47
	v_mul_f32_e32 v48, 0x3fb8aa3b, v48
	v_mul_f32_e32 v49, 0x3fb8aa3b, v49
	v_exp_f32_e32 v44, v26
	v_exp_f32_e32 v45, v1
	v_exp_f32_e32 v46, v46
	v_exp_f32_e32 v47, v47
	v_exp_f32_e32 v48, v48
	v_exp_f32_e32 v49, v49
	ds_bpermute_b32 v0, v92, v24
	ds_bpermute_b32 v1, v92, v25
	ds_bpermute_b32 v26, v92, v44
	ds_bpermute_b32 v27, v92, v45
	ds_bpermute_b32 v52, v92, v46
	ds_bpermute_b32 v53, v92, v47
	ds_bpermute_b32 v50, v92, v48
	ds_bpermute_b32 v51, v92, v49
	s_and_saveexec_b64 s[16:17], s[6:7]
	s_cbranch_execz .LBB0_886
	v_mul_f32_e32 v62, 0x3fb8aa3b, v62
	v_mul_f32_e32 v63, 0x3fb8aa3b, v63
	v_mul_f32_e32 v64, 0x3fb8aa3b, v64
	v_mul_f32_e32 v65, 0x3fb8aa3b, v65
	v_exp_f32_e32 v62, v62
	v_exp_f32_e32 v63, v63
	v_exp_f32_e32 v64, v64
	v_exp_f32_e32 v65, v65
	v_mul_f32_e32 v61, 0x3fb8aa3b, v61
	ds_write_b128 v93, v[62:65] offset:34816
	v_exp_f32_e32 v62, v61
	v_mul_f32_e32 v61, 0x3fb8aa3b, v66
	v_exp_f32_e32 v63, v61
	v_mul_f32_e32 v61, 0x3fb8aa3b, v67
	v_exp_f32_e32 v64, v61
	v_mul_f32_e32 v61, 0x3fb8aa3b, v68
	v_exp_f32_e32 v65, v61
	ds_write_b128 v93, v[62:65] offset:34832
.LBB0_886:
	s_or_b64 exec, exec, s[16:17]
	v_mul_f32_e32 v59, 0x3fb8aa3b, v59
	v_mul_f32_e32 v58, 0x3fb8aa3b, v58
	v_mul_f32_e32 v57, 0x3fb8aa3b, v57
	s_waitcnt vmcnt(8)
	v_lshlrev_b32_e32 v62, 16, v16
	v_and_b32_e32 v63, 0xffff0000, v16
	v_exp_f32_e32 v61, v59
	v_exp_f32_e32 v58, v58
	v_exp_f32_e32 v59, v57
	v_rcp_f32_e32 v66, v24
	v_rcp_f32_e32 v67, v25
	v_pk_mul_f32 v[24:25], v[24:25], v[62:63]
	v_rcp_f32_e32 v62, v44
	v_rcp_f32_e32 v63, v45
	v_lshlrev_b32_e32 v16, 16, v17
	v_and_b32_e32 v17, 0xffff0000, v17
	v_mul_f32_e32 v56, 0x3fb8aa3b, v56
	v_mul_f32_e32 v55, 0x3fb8aa3b, v55
	v_exp_f32_e32 v56, v56
	v_exp_f32_e32 v57, v55
	v_pk_mul_f32 v[44:45], v[44:45], v[16:17]
	v_pk_add_f32 v[16:17], v[58:59], 1.0 op_sel_hi:[1,0] neg_lo:[1,0] neg_hi:[1,0]
	v_mul_f32_e32 v60, 0x3fb8aa3b, v60
	v_pk_mul_f32 v[58:59], v[16:17], v[62:63]
	v_rcp_f32_e32 v16, v46
	v_rcp_f32_e32 v17, v47
	v_mul_f32_e32 v54, 0x3fb8aa3b, v54
	v_mul_f32_e32 v3, 0x3fb8aa3b, v3
	v_exp_f32_e32 v60, v60
	v_exp_f32_e32 v54, v54
	v_exp_f32_e32 v55, v3
	v_pk_add_f32 v[56:57], v[56:57], 1.0 op_sel_hi:[1,0] neg_lo:[1,0] neg_hi:[1,0]
	v_lshlrev_b32_e32 v64, 16, v18
	v_pk_mul_f32 v[56:57], v[56:57], v[16:17]
	v_rcp_f32_e32 v16, v48
	v_rcp_f32_e32 v17, v49
	v_and_b32_e32 v65, 0xffff0000, v18
	v_lshlrev_b32_e32 v18, 16, v19
	v_and_b32_e32 v19, 0xffff0000, v19
	v_pk_add_f32 v[60:61], v[60:61], 1.0 op_sel_hi:[1,0] neg_lo:[1,0] neg_hi:[1,0]
	v_pk_mul_f32 v[46:47], v[46:47], v[64:65]
	v_pk_mul_f32 v[48:49], v[48:49], v[18:19]
	v_pk_add_f32 v[18:19], v[54:55], 1.0 op_sel_hi:[1,0] neg_lo:[1,0] neg_hi:[1,0]
	v_pk_mul_f32 v[60:61], v[60:61], v[66:67]
	v_pk_mul_f32 v[54:55], v[18:19], v[16:17]
	v_cvt_pk_bf16_f32 v16, v24, v25
	v_cvt_pk_bf16_f32 v17, v44, v45
	v_cvt_pk_bf16_f32 v18, v46, v47
	v_cvt_pk_bf16_f32 v19, v48, v49
	s_waitcnt lgkmcnt(6)
	v_pk_mul_f32 v[0:1], v[60:61], v[0:1]
	s_waitcnt lgkmcnt(4)
	v_pk_mul_f32 v[26:27], v[58:59], v[26:27]
	s_waitcnt lgkmcnt(2)
	v_pk_mul_f32 v[52:53], v[56:57], v[52:53]
	s_waitcnt lgkmcnt(0)
	v_pk_mul_f32 v[50:51], v[54:55], v[50:51]
	ds_write_b128 v94, v[16:19]
	v_cvt_pk_bf16_f32 v16, v60, v61
	v_cvt_pk_bf16_f32 v17, v58, v59
	v_cvt_pk_bf16_f32 v18, v56, v57
	v_cvt_pk_bf16_f32 v19, v54, v55
	ds_write_b128 v94, v[16:19] offset:8704
	v_cvt_pk_bf16_f32 v16, v0, v1
	v_cvt_pk_bf16_f32 v17, v26, v27
	v_cvt_pk_bf16_f32 v18, v52, v53
	v_cvt_pk_bf16_f32 v19, v50, v51
	ds_write_b128 v94, v[16:19] offset:17408
.LBB0_887:
	s_or_b64 exec, exec, s[56:57]
	s_add_i32 s58, s28, -1
	s_min_i32 s16, s58, s35
	s_lshl_b32 s16, s16, 5
	v_or_b32_e32 v0, s16, v89
	v_xad_u32 v1, v0, -1, s74
	v_cndmask_b32_e64 v0, v1, v0, s[4:5]
	v_add_u32_e32 v1, s16, v90
	v_xad_u32 v3, v1, -1, s74
	v_add_u32_e32 v0, s73, v0
	v_cndmask_b32_e64 v3, v3, v1, s[4:5]
	v_ashrrev_i32_e32 v1, 31, v0
	s_waitcnt vmcnt(7)
	ds_write_b128 v95, v[8:11] offset:26112
	v_mad_i64_i32 v[8:9], s[16:17], v0, s89, v[80:81]
	v_lshlrev_b64 v[0:1], 11, v[0:1]
	v_lshl_add_u64 v[0:1], v[82:83], 0, v[0:1]
	global_load_dwordx4 v[16:19], v[8:9], off
	global_load_dwordx4 v[24:27], v[0:1], off
	v_add_u32_e32 v0, s73, v3
	v_mad_i64_i32 v[0:1], s[16:17], v0, s89, v[84:85]
	global_load_dwordx4 v[8:11], v[0:1], off
	v_add_u32_e32 v0, 0x800, v97
	s_waitcnt lgkmcnt(0)
	s_barrier
	ds_read_b64_tr_b16 v[60:61], v96 offset:26112
	ds_read_b64_tr_b16 v[62:63], v96 offset:30464
	ds_read_b64 v[56:57], v97
	ds_read_b64 v[58:59], v97 offset:32
	ds_read_b64 v[44:45], v97 offset:64
	ds_read_b64 v[46:47], v97 offset:96
	ds_read_b64 v[52:53], v0 offset:256
	ds_read_b64 v[54:55], v0 offset:288
	ds_read_b64 v[48:49], v0 offset:320
	ds_read_b64 v[50:51], v0 offset:352
	v_add_u32_e32 v0, 0x2000, v98
	v_add_u32_e32 v1, 0x2800, v98
	ds_read_b64 v[64:65], v0 offset:512
	ds_read_b64 v[66:67], v0 offset:544
	ds_read_b64 v[68:69], v1 offset:768
	ds_read_b64 v[70:71], v1 offset:800
	ds_read_b64 v[76:77], v0 offset:576
	ds_read_b64 v[78:79], v0 offset:608
	ds_read_b64 v[112:113], v1 offset:832
	ds_read_b64 v[114:115], v1 offset:864
	s_waitcnt lgkmcnt(6)
	v_mfma_f32_16x16x32_bf16 v[72:75], v[64:67], v[56:59], 0
	v_mov_b32_e32 v0, s93
	s_waitcnt lgkmcnt(4)
	v_mfma_f32_16x16x32_bf16 v[68:71], v[68:71], v[52:55], 0
	s_waitcnt lgkmcnt(2)
	v_mfma_f32_16x16x32_bf16 v[72:75], v[76:79], v[44:47], v[72:75]
	s_waitcnt lgkmcnt(0)
	v_mfma_f32_16x16x32_bf16 v[68:71], v[112:115], v[48:51], v[68:71]
	v_mov_b32_e32 v112, s93
	s_nop 4
	v_cndmask_b32_e64 v0, v72, v0, s[8:9]
	v_cndmask_b32_e64 v0, v0, v72, s[10:11]
	v_mfma_f32_16x16x32_bf16 v[64:67], v[64:67], v[52:55], 0
	v_cndmask_b32_e64 v3, v74, 0, s[12:13]
	v_cndmask_b32_e64 v1, v68, v112, s[8:9]
	v_cndmask_b32_e64 v68, v1, v68, s[10:11]
	v_cndmask_b32_e64 v1, 0, v73, s[10:11]
	v_cndmask_b32_e64 v72, v75, 0, s[14:15]
	v_mfma_f32_16x16x32_bf16 v[64:67], v[76:79], v[48:51], v[64:67]
	v_cvt_pk_bf16_f32 v0, v0, v1
	v_cvt_pk_bf16_f32 v1, v3, v72
	ds_read_b128 v[72:75], v99 offset:35328
	ds_read_b128 v[76:79], v99 offset:35392
	v_cndmask_b32_e64 v69, 0, v69, s[10:11]
	v_cndmask_b32_e64 v70, v70, 0, s[12:13]
	v_cndmask_b32_e64 v71, v71, 0, s[14:15]
	v_mov_b32_e32 v3, v2
	v_cvt_pk_bf16_f32 v64, v64, v65
	v_cvt_pk_bf16_f32 v65, v66, v67
	v_cvt_pk_bf16_f32 v66, v68, v69
	v_cvt_pk_bf16_f32 v67, v70, v71
	v_mfma_f32_16x16x32_bf16 v[68:71], v[60:63], v[0:3], 0
	s_waitcnt lgkmcnt(1)
	v_pk_mul_f32 v[0:1], v[42:43], v[74:75]
	s_waitcnt lgkmcnt(0)
	v_pk_mul_f32 v[78:79], v[38:39], v[78:79]
	v_pk_mul_f32 v[74:75], v[36:37], v[76:77]
	v_pk_mul_f32 v[72:73], v[40:41], v[72:73]
	v_cvt_pk_bf16_f32 v74, v74, v75
	v_cvt_pk_bf16_f32 v75, v78, v79
	ds_read_b128 v[76:79], v99 offset:35456
	ds_read_b128 v[112:115], v99 offset:35520
	v_cvt_pk_bf16_f32 v72, v72, v73
	v_cvt_pk_bf16_f32 v73, v0, v1
	v_mfma_f32_16x16x32_bf16 v[64:67], v[60:63], v[64:67], 0
	s_waitcnt lgkmcnt(1)
	v_pk_mul_f32 v[0:1], v[30:31], v[78:79]
	s_waitcnt lgkmcnt(0)
	v_pk_mul_f32 v[114:115], v[34:35], v[114:115]
	v_pk_mul_f32 v[78:79], v[32:33], v[112:113]
	v_pk_mul_f32 v[76:77], v[28:29], v[76:77]
	v_cvt_pk_bf16_f32 v78, v78, v79
	v_cvt_pk_bf16_f32 v79, v114, v115
	ds_read_b128 v[112:115], v99 offset:34816
	ds_read_b64_tr_b16 v[118:119], v100 offset:19712
	ds_read_b64_tr_b16 v[116:117], v100 offset:17408
	ds_read_b64_tr_b16 v[120:121], v100 offset:17440
	v_cvt_pk_bf16_f32 v76, v76, v77
	s_waitcnt lgkmcnt(3)
	v_pk_mul_f32 v[42:43], v[42:43], v[114:115]
	v_pk_mul_f32 v[40:41], v[40:41], v[112:113]
	ds_read_b128 v[112:115], v99 offset:34880
	ds_read_b64_tr_b16 v[122:123], v100 offset:19744
	v_cvt_pk_bf16_f32 v77, v0, v1
	v_mfma_f32_16x16x32_bf16 v[56:59], v[72:75], v[56:59], v[68:71]
	v_xor_b32_e32 v1, 0xffffffef, v88
	s_waitcnt lgkmcnt(1)
	v_pk_mul_f32 v[38:39], v[38:39], v[114:115]
	v_pk_mul_f32 v[36:37], v[36:37], v[112:113]
	v_mfma_f32_16x16x32_bf16 v[40:43], v[116:119], v[60:63], v[40:43]
	ds_read_b128 v[112:115], v99 offset:34944
	ds_read_b64_tr_b16 v[116:117], v100 offset:17472
	ds_read_b64_tr_b16 v[118:119], v100 offset:19776
	v_add_u32_e32 v0, 16, v88
	v_cndmask_b32_e64 v3, v111, v88, s[4:5]
	v_mfma_f32_16x16x32_bf16 v[52:55], v[72:75], v[52:55], v[64:67]
	s_waitcnt lgkmcnt(2)
	v_pk_mul_f32 v[30:31], v[30:31], v[114:115]
	v_pk_mul_f32 v[28:29], v[28:29], v[112:113]
	v_add_u32_e32 v1, s74, v1
	v_mfma_f32_16x16x32_bf16 v[44:47], v[76:79], v[44:47], v[56:59]
	s_waitcnt lgkmcnt(0)
	v_mfma_f32_16x16x32_bf16 v[28:31], v[116:119], v[60:63], v[28:31]
	ds_read_b128 v[112:115], v99 offset:35008
	ds_read_b64_tr_b16 v[116:117], v100 offset:17504
	ds_read_b64_tr_b16 v[118:119], v100 offset:19808
	s_waitcnt lgkmcnt(2)
	v_pk_mul_f32 v[34:35], v[34:35], v[114:115]
	v_mfma_f32_16x16x32_bf16 v[48:51], v[76:79], v[48:51], v[52:55]
	v_mul_f32_e64 v32, v32, v112
	v_mul_f32_e64 v33, v33, v113
	s_nop 0
	v_cndmask_b32_e64 v52, v1, v0, s[4:5]
	v_cvt_pk_bf16_f32 v1, v46, v47
	v_add_u32_e32 v46, s73, v3
	v_ashrrev_i32_e32 v47, 31, v46
	v_lshlrev_b64 v[46:47], 11, v[46:47]
	v_cvt_pk_bf16_f32 v0, v44, v45
	v_lshl_add_u64 v[46:47], v[86:87], 0, v[46:47]
	v_mfma_f32_16x16x32_bf16 v[36:39], v[120:123], v[60:63], v[36:39]
	global_store_dwordx2 v[46:47], v[0:1], off
	v_add_u32_e32 v0, s73, v52
	v_ashrrev_i32_e32 v1, 31, v0
	s_waitcnt lgkmcnt(0)
	v_mfma_f32_16x16x32_bf16 v[32:35], v[116:119], v[60:63], v[32:35]
	v_lshlrev_b64 v[0:1], 11, v[0:1]
	v_cvt_pk_bf16_f32 v44, v48, v49
	v_cvt_pk_bf16_f32 v45, v50, v51
	v_lshl_add_u64 v[0:1], v[86:87], 0, v[0:1]
	global_store_dwordx2 v[0:1], v[44:45], off
	s_and_saveexec_b64 s[56:57], vcc
	s_cbranch_execz .LBB0_882
	s_waitcnt vmcnt(8)
	v_cvt_f32_f16_e32 v60, v20
	v_cvt_f32_f16_sdwa v59, v20 dst_sel:DWORD dst_unused:UNUSED_PAD src0_sel:WORD_1
	v_cvt_f32_f16_e32 v58, v21
	v_cvt_f32_f16_sdwa v57, v21 dst_sel:DWORD dst_unused:UNUSED_PAD src0_sel:WORD_1
	v_add_f32_dpp v0, v60, v60 row_shr:1 row_mask:0xf bank_mask:0xf bound_ctrl:1
	v_add_f32_dpp v1, v59, v59 row_shr:1 row_mask:0xf bank_mask:0xf bound_ctrl:1
	v_mov_b32_e32 v46, v2
	v_add_f32_dpp v0, v0, v0 row_shr:2 row_mask:0xf bank_mask:0xf bound_ctrl:1
	v_add_f32_dpp v1, v1, v1 row_shr:2 row_mask:0xf bank_mask:0xf bound_ctrl:1
	v_cvt_f32_f16_e32 v56, v22
	v_add_f32_dpp v0, v0, v0 row_shr:4 row_mask:0xf bank_mask:0xf bound_ctrl:1
	v_add_f32_dpp v20, v58, v58 row_shr:1 row_mask:0xf bank_mask:0xf bound_ctrl:1
	v_add_f32_dpp v1, v1, v1 row_shr:4 row_mask:0xf bank_mask:0xf bound_ctrl:1
	v_add_f32_dpp v0, v0, v0 row_shr:8 row_mask:0xf bank_mask:0xf bound_ctrl:1
	v_add_f32_dpp v20, v20, v20 row_shr:2 row_mask:0xf bank_mask:0xf bound_ctrl:1
	v_add_f32_dpp v1, v1, v1 row_shr:8 row_mask:0xf bank_mask:0xf bound_ctrl:1
	v_mov_b32_dpp v46, v0 row_bcast:15 row_mask:0xa bank_mask:0xf
	v_add_f32_e32 v62, v0, v46
	v_mov_b32_e32 v0, v2
	v_cvt_f32_f16_sdwa v55, v22 dst_sel:DWORD dst_unused:UNUSED_PAD src0_sel:WORD_1
	v_add_f32_dpp v21, v57, v57 row_shr:1 row_mask:0xf bank_mask:0xf bound_ctrl:1
	v_add_f32_dpp v20, v20, v20 row_shr:4 row_mask:0xf bank_mask:0xf bound_ctrl:1
	v_mov_b32_dpp v0, v1 row_bcast:15 row_mask:0xa bank_mask:0xf
	v_add_f32_dpp v21, v21, v21 row_shr:2 row_mask:0xf bank_mask:0xf bound_ctrl:1
	v_add_f32_dpp v20, v20, v20 row_shr:8 row_mask:0xf bank_mask:0xf bound_ctrl:1
	v_add_f32_e32 v63, v1, v0
	v_mov_b32_e32 v0, v2
	v_cvt_f32_f16_e32 v54, v23
	v_add_f32_dpp v22, v56, v56 row_shr:1 row_mask:0xf bank_mask:0xf bound_ctrl:1
	v_add_f32_dpp v21, v21, v21 row_shr:4 row_mask:0xf bank_mask:0xf bound_ctrl:1
	v_mov_b32_dpp v0, v20 row_bcast:15 row_mask:0xa bank_mask:0xf
	v_add_f32_dpp v22, v22, v22 row_shr:2 row_mask:0xf bank_mask:0xf bound_ctrl:1
	v_add_f32_dpp v21, v21, v21 row_shr:8 row_mask:0xf bank_mask:0xf bound_ctrl:1
	v_add_f32_e32 v64, v20, v0
	v_mov_b32_e32 v0, v2
	v_cvt_f32_f16_sdwa v3, v23 dst_sel:DWORD dst_unused:UNUSED_PAD src0_sel:WORD_1
	v_add_f32_dpp v23, v55, v55 row_shr:1 row_mask:0xf bank_mask:0xf bound_ctrl:1
	v_add_f32_dpp v22, v22, v22 row_shr:4 row_mask:0xf bank_mask:0xf bound_ctrl:1
	v_mov_b32_dpp v0, v21 row_bcast:15 row_mask:0xa bank_mask:0xf
	v_add_f32_dpp v23, v23, v23 row_shr:2 row_mask:0xf bank_mask:0xf bound_ctrl:1
	v_add_f32_dpp v22, v22, v22 row_shr:8 row_mask:0xf bank_mask:0xf bound_ctrl:1
	v_add_f32_e32 v65, v21, v0
	v_mov_b32_e32 v0, v2
	v_add_f32_dpp v44, v54, v54 row_shr:1 row_mask:0xf bank_mask:0xf bound_ctrl:1
	v_add_f32_dpp v23, v23, v23 row_shr:4 row_mask:0xf bank_mask:0xf bound_ctrl:1
	v_mov_b32_dpp v0, v22 row_bcast:15 row_mask:0xa bank_mask:0xf
	ds_bpermute_b32 v1, v91, v62
	v_add_f32_dpp v44, v44, v44 row_shr:2 row_mask:0xf bank_mask:0xf bound_ctrl:1
	v_add_f32_dpp v23, v23, v23 row_shr:8 row_mask:0xf bank_mask:0xf bound_ctrl:1
	v_add_f32_e32 v61, v22, v0
	v_mov_b32_e32 v0, v2
	v_add_f32_dpp v44, v44, v44 row_shr:4 row_mask:0xf bank_mask:0xf bound_ctrl:1
	v_add_f32_dpp v45, v3, v3 row_shr:1 row_mask:0xf bank_mask:0xf bound_ctrl:1
	v_mov_b32_dpp v0, v23 row_bcast:15 row_mask:0xa bank_mask:0xf
	v_add_f32_dpp v44, v44, v44 row_shr:8 row_mask:0xf bank_mask:0xf bound_ctrl:1
	v_add_f32_e32 v66, v23, v0
	v_mov_b32_e32 v0, v2
	v_add_f32_dpp v45, v45, v45 row_shr:2 row_mask:0xf bank_mask:0xf bound_ctrl:1
	ds_bpermute_b32 v22, v91, v64
	v_mov_b32_dpp v0, v44 row_bcast:15 row_mask:0xa bank_mask:0xf
	v_add_f32_e32 v67, v44, v0
	s_waitcnt lgkmcnt(1)
	v_sub_f32_e32 v0, v62, v1
	ds_bpermute_b32 v1, v91, v63
	v_med3_f32 v0, v0, s69, v189
	v_add_f32_dpp v45, v45, v45 row_shr:4 row_mask:0xf bank_mask:0xf bound_ctrl:1
	v_mul_f32_e32 v0, 0x3fb8aa3b, v0
	v_exp_f32_e32 v20, v0
	v_add_f32_dpp v45, v45, v45 row_shr:8 row_mask:0xf bank_mask:0xf bound_ctrl:1
	v_mov_b32_e32 v0, v2
	s_waitcnt lgkmcnt(0)
	v_sub_f32_e32 v1, v63, v1
	v_med3_f32 v1, v1, s69, v189
	v_mov_b32_dpp v0, v45 row_bcast:15 row_mask:0xa bank_mask:0xf
	v_add_f32_e32 v68, v45, v0
	v_mul_f32_e32 v1, 0x3fb8aa3b, v1
	v_exp_f32_e32 v21, v1
	ds_bpermute_b32 v1, v91, v65
	ds_bpermute_b32 v46, v91, v61
	ds_bpermute_b32 v47, v91, v66
	ds_bpermute_b32 v48, v91, v67
	ds_bpermute_b32 v49, v91, v68
	v_sub_f32_e32 v22, v64, v22
	s_waitcnt lgkmcnt(4)
	v_sub_f32_e32 v1, v65, v1
	s_waitcnt lgkmcnt(3)
	v_sub_f32_e32 v46, v61, v46
	s_waitcnt lgkmcnt(2)
	v_sub_f32_e32 v47, v66, v47
	s_waitcnt lgkmcnt(1)
	v_sub_f32_e32 v48, v67, v48
	s_waitcnt lgkmcnt(0)
	v_sub_f32_e32 v49, v68, v49
	v_med3_f32 v22, v22, s69, v189
	v_med3_f32 v1, v1, s69, v189
	v_med3_f32 v46, v46, s69, v189
	v_med3_f32 v47, v47, s69, v189
	v_med3_f32 v48, v48, s69, v189
	v_med3_f32 v49, v49, s69, v189
	v_mul_f32_e32 v22, 0x3fb8aa3b, v22
	v_mul_f32_e32 v1, 0x3fb8aa3b, v1
	v_mul_f32_e32 v46, 0x3fb8aa3b, v46
	v_mul_f32_e32 v47, 0x3fb8aa3b, v47
	v_mul_f32_e32 v48, 0x3fb8aa3b, v48
	v_mul_f32_e32 v49, 0x3fb8aa3b, v49
	v_exp_f32_e32 v44, v22
	v_exp_f32_e32 v45, v1
	v_exp_f32_e32 v46, v46
	v_exp_f32_e32 v47, v47
	v_exp_f32_e32 v48, v48
	v_exp_f32_e32 v49, v49
	ds_bpermute_b32 v0, v92, v20
	ds_bpermute_b32 v1, v92, v21
	ds_bpermute_b32 v22, v92, v44
	ds_bpermute_b32 v23, v92, v45
	ds_bpermute_b32 v52, v92, v46
	ds_bpermute_b32 v53, v92, v47
	ds_bpermute_b32 v50, v92, v48
	ds_bpermute_b32 v51, v92, v49
	s_and_saveexec_b64 s[16:17], s[6:7]
	s_cbranch_execz .LBB0_881
	v_mul_f32_e32 v62, 0x3fb8aa3b, v62
	v_mul_f32_e32 v63, 0x3fb8aa3b, v63
	v_mul_f32_e32 v64, 0x3fb8aa3b, v64
	v_mul_f32_e32 v65, 0x3fb8aa3b, v65
	v_exp_f32_e32 v62, v62
	v_exp_f32_e32 v63, v63
	v_exp_f32_e32 v64, v64
	v_exp_f32_e32 v65, v65
	v_mul_f32_e32 v61, 0x3fb8aa3b, v61
	ds_write_b128 v101, v[62:65]
	v_exp_f32_e32 v62, v61
	v_mul_f32_e32 v61, 0x3fb8aa3b, v66
	v_exp_f32_e32 v63, v61
	v_mul_f32_e32 v61, 0x3fb8aa3b, v67
	v_exp_f32_e32 v64, v61
	v_mul_f32_e32 v61, 0x3fb8aa3b, v68
	v_exp_f32_e32 v65, v61
	ds_write_b128 v101, v[62:65] offset:16
	s_branch .LBB0_881
